# adds unit-start peel (first K iteration of every non-first unit: SrcC=0 instead of zeroing 128 accumulators, first two staged-load waits let the epilogue stores stay in flight)
# speedup vs baseline: 1.0083x; 1.0022x over previous
.LBB0_142:
	s_lshl_b32 s86, s85, 20
	s_and_b64 s[0:1], s[40:41], exec
	s_cselect_b32 s0, s86, s4
	s_lshl_b32 s87, s84, 20
	s_and_b64 s[6:7], s[40:41], exec
	s_cselect_b32 s1, s87, s5
	s_add_i32 s4, s4, 0x84000
	s_add_i32 s5, s5, 0x8000
	s_mov_b32 s6, -2
	s_cmp_eq_u32 s82, 1
	s_cbranch_scc0 .Lpeel_p1
	v_mov_b32_e32 v0, 0
	v_mov_b32_e32 v1, v0
	v_mov_b32_e32 v2, v0
	v_mov_b32_e32 v3, v0
	v_mov_b32_e32 v8, v0
	v_mov_b32_e32 v9, v0
	v_mov_b32_e32 v10, v0
	v_mov_b32_e32 v11, v0
	v_mov_b32_e32 v32, v0
	v_mov_b32_e32 v33, v0
	s_waitcnt lgkmcnt(1)
	v_mov_b32_e32 v34, v0
	v_mov_b32_e32 v35, v0
	v_mov_b32_e32 v40, v0
	v_mov_b32_e32 v41, v0
	v_mov_b32_e32 v42, v0
	v_mov_b32_e32 v43, v0
	s_waitcnt vmcnt(5)
	v_mov_b32_e32 v48, v0
	v_mov_b32_e32 v49, v0
	v_mov_b32_e32 v50, v0
	v_mov_b32_e32 v51, v0
	s_waitcnt vmcnt(3)
	v_mov_b32_e32 v56, v0
	v_mov_b32_e32 v57, v0
	v_mov_b32_e32 v58, v0
	v_mov_b32_e32 v59, v0
	v_mov_b32_e32 v64, v0
	v_mov_b32_e32 v65, v0
	v_mov_b32_e32 v66, v0
	v_mov_b32_e32 v67, v0
	v_mov_b32_e32 v72, v0
	v_mov_b32_e32 v73, v0
	v_mov_b32_e32 v74, v0
	v_mov_b32_e32 v75, v0
	v_mov_b32_e32 v4, v0
	v_mov_b32_e32 v5, v0
	v_mov_b32_e32 v6, v0
	v_mov_b32_e32 v7, v0
	v_mov_b32_e32 v12, v0
	v_mov_b32_e32 v13, v0
	v_mov_b32_e32 v14, v0
	v_mov_b32_e32 v15, v0
	s_waitcnt lgkmcnt(0)
	v_mov_b32_e32 v36, v0
	v_mov_b32_e32 v37, v0
	v_mov_b32_e32 v38, v0
	v_mov_b32_e32 v39, v0
	v_mov_b32_e32 v44, v0
	v_mov_b32_e32 v45, v0
	v_mov_b32_e32 v46, v0
	v_mov_b32_e32 v47, v0
	v_mov_b32_e32 v52, v0
	v_mov_b32_e32 v53, v0
	v_mov_b32_e32 v54, v0
	v_mov_b32_e32 v55, v0
	s_waitcnt vmcnt(2)
	v_mov_b32_e32 v60, v0
	v_mov_b32_e32 v61, v0
	v_mov_b32_e32 v62, v0
	v_mov_b32_e32 v63, v0
	v_mov_b32_e32 v68, v0
	v_mov_b32_e32 v69, v0
	v_mov_b32_e32 v70, v0
	v_mov_b32_e32 v71, v0
	v_mov_b32_e32 v76, v0
	v_mov_b32_e32 v77, v0
	v_mov_b32_e32 v78, v0
	v_mov_b32_e32 v79, v0
	v_mov_b32_e32 v104, v0
	v_mov_b32_e32 v105, v0
	v_mov_b32_e32 v106, v0
	v_mov_b32_e32 v107, v0
	v_mov_b32_e32 v112, v0
	v_mov_b32_e32 v113, v0
	v_mov_b32_e32 v114, v0
	v_mov_b32_e32 v115, v0
	v_mov_b32_e32 v120, v0
	v_mov_b32_e32 v121, v0
	v_mov_b32_e32 v122, v0
	v_mov_b32_e32 v123, v0
	v_mov_b32_e32 v128, v0
	v_mov_b32_e32 v129, v0
	v_mov_b32_e32 v130, v0
	v_mov_b32_e32 v131, v0
	v_mov_b32_e32 v136, v0
	v_mov_b32_e32 v137, v0
	v_mov_b32_e32 v138, v0
	v_mov_b32_e32 v139, v0
	v_mov_b32_e32 v144, v0
	v_mov_b32_e32 v145, v0
	v_mov_b32_e32 v146, v0
	v_mov_b32_e32 v147, v0
	v_mov_b32_e32 v156, v0
	v_mov_b32_e32 v157, v0
	v_mov_b32_e32 v158, v0
	v_mov_b32_e32 v159, v0
	v_mov_b32_e32 v172, v0
	v_mov_b32_e32 v173, v0
	v_mov_b32_e32 v174, v0
	v_mov_b32_e32 v175, v0
	v_mov_b32_e32 v108, v0
	v_mov_b32_e32 v109, v0
	v_mov_b32_e32 v110, v0
	v_mov_b32_e32 v111, v0
	v_mov_b32_e32 v116, v0
	v_mov_b32_e32 v117, v0
	v_mov_b32_e32 v118, v0
	v_mov_b32_e32 v119, v0
	v_mov_b32_e32 v124, v0
	v_mov_b32_e32 v125, v0
	v_mov_b32_e32 v126, v0
	v_mov_b32_e32 v127, v0
	v_mov_b32_e32 v132, v0
	v_mov_b32_e32 v133, v0
	v_mov_b32_e32 v134, v0
	v_mov_b32_e32 v135, v0
	v_mov_b32_e32 v140, v0
	v_mov_b32_e32 v141, v0
	v_mov_b32_e32 v142, v0
	v_mov_b32_e32 v143, v0
	v_mov_b32_e32 v148, v0
	v_mov_b32_e32 v149, v0
	v_mov_b32_e32 v150, v0
	v_mov_b32_e32 v151, v0
	v_mov_b32_e32 v164, v0
	v_mov_b32_e32 v165, v0
	v_mov_b32_e32 v166, v0
	v_mov_b32_e32 v167, v0
	v_mov_b32_e32 v180, v0
	v_mov_b32_e32 v181, v0
	v_mov_b32_e32 v182, v0
	v_mov_b32_e32 v183, v0
	s_branch .LBB0_143
.Lpeel_p1:
	s_waitcnt lgkmcnt(0)
	v_add_u32_e32 v28, 0x10000, v83
	v_add_u32_e32 v80, 0x14000, v83
	ds_read_b128 v[16:19], v28
	ds_read_b128 v[20:23], v28 offset:1024
	ds_read_b128 v[24:27], v28 offset:2048
	ds_read_b128 v[28:31], v28 offset:3072
	ds_read_b128 v[152:155], v80
	ds_read_b128 v[160:163], v80 offset:1024
	ds_read_b128 v[168:171], v80 offset:2048
	ds_read_b128 v[176:179], v80 offset:3072
	s_add_i32 s7, s4, 0xfff84000
	s_cmp_eq_u32 s6, 28
	s_cselect_b32 s17, s0, s7
	s_cselect_b32 s16, s1, s5
	s_or_b32 s7, s17, 0x4000
	ds_read_b128 v[192:195], v245
	ds_read_b128 v[196:199], v245 offset:1024
	ds_read_b128 v[200:203], v245 offset:2048
	ds_read_b128 v[204:207], v245 offset:3072
	ds_read_b128 v[220:223], v245 offset:4096
	ds_read_b128 v[224:227], v245 offset:5120
	ds_read_b128 v[228:231], v245 offset:6144
	ds_read_b128 v[246:249], v245 offset:7168
	s_mov_b32 m0, s79
	s_nop 0
	buffer_load_dwordx4 v242, s[24:27], s4 offen lds
	s_nop 0
	s_mov_b32 m0, s83
	s_nop 0
	buffer_load_dwordx4 v243, s[24:27], s4 offen lds
	s_waitcnt vmcnt(24)
	s_waitcnt lgkmcnt(0)
	s_barrier
	s_setprio 1
	s_waitcnt lgkmcnt(7)
	v_mfma_f32_16x16x32_bf16 v[180:183], v[16:19], v[192:195], 0
	v_mfma_f32_16x16x32_bf16 v[164:167], v[24:27], v[192:195], 0
	s_waitcnt lgkmcnt(5)
	v_mfma_f32_16x16x32_bf16 v[148:151], v[16:19], v[200:203], 0
	v_mfma_f32_16x16x32_bf16 v[140:143], v[24:27], v[200:203], 0
	s_waitcnt lgkmcnt(3)
	v_mfma_f32_16x16x32_bf16 v[132:135], v[16:19], v[220:223], 0
	v_mfma_f32_16x16x32_bf16 v[124:127], v[24:27], v[220:223], 0
	s_waitcnt lgkmcnt(1)
	v_mfma_f32_16x16x32_bf16 v[116:119], v[16:19], v[228:231], 0
	v_mfma_f32_16x16x32_bf16 v[108:111], v[24:27], v[228:231], 0
	v_mfma_f32_16x16x32_bf16 v[180:183], v[20:23], v[196:199], v[180:183]
	v_mfma_f32_16x16x32_bf16 v[164:167], v[28:31], v[196:199], v[164:167]
	v_mfma_f32_16x16x32_bf16 v[148:151], v[20:23], v[204:207], v[148:151]
	v_mfma_f32_16x16x32_bf16 v[140:143], v[28:31], v[204:207], v[140:143]
	v_mfma_f32_16x16x32_bf16 v[132:135], v[20:23], v[224:227], v[132:135]
	v_mfma_f32_16x16x32_bf16 v[124:127], v[28:31], v[224:227], v[124:127]
	s_waitcnt lgkmcnt(0)
	v_mfma_f32_16x16x32_bf16 v[116:119], v[20:23], v[246:249], v[116:119]
	v_mfma_f32_16x16x32_bf16 v[108:111], v[28:31], v[246:249], v[108:111]
	s_setprio 0
	s_setprio 1
	v_mfma_f32_16x16x32_bf16 v[172:175], v[152:155], v[192:195], 0
	v_mfma_f32_16x16x32_bf16 v[156:159], v[168:171], v[192:195], 0
	v_mfma_f32_16x16x32_bf16 v[144:147], v[152:155], v[200:203], 0
	v_mfma_f32_16x16x32_bf16 v[136:139], v[168:171], v[200:203], 0
	v_mfma_f32_16x16x32_bf16 v[128:131], v[152:155], v[220:223], 0
	v_mfma_f32_16x16x32_bf16 v[120:123], v[168:171], v[220:223], 0
	v_mfma_f32_16x16x32_bf16 v[112:115], v[152:155], v[228:231], 0
	v_mfma_f32_16x16x32_bf16 v[104:107], v[168:171], v[228:231], 0
	v_mfma_f32_16x16x32_bf16 v[172:175], v[160:163], v[196:199], v[172:175]
	v_mfma_f32_16x16x32_bf16 v[156:159], v[176:179], v[196:199], v[156:159]
	v_mfma_f32_16x16x32_bf16 v[144:147], v[160:163], v[204:207], v[144:147]
	v_mfma_f32_16x16x32_bf16 v[136:139], v[176:179], v[204:207], v[136:139]
	v_mfma_f32_16x16x32_bf16 v[128:131], v[160:163], v[224:227], v[128:131]
	v_mfma_f32_16x16x32_bf16 v[120:123], v[176:179], v[224:227], v[120:123]
	v_mfma_f32_16x16x32_bf16 v[112:115], v[160:163], v[246:249], v[112:115]
	v_mfma_f32_16x16x32_bf16 v[104:107], v[176:179], v[246:249], v[104:107]
	s_setprio 0
	s_barrier
	ds_read_b128 v[192:195], v245 offset:16384
	ds_read_b128 v[196:199], v245 offset:17408
	ds_read_b128 v[200:203], v245 offset:18432
	ds_read_b128 v[204:207], v245 offset:19456
	ds_read_b128 v[220:223], v245 offset:20480
	ds_read_b128 v[224:227], v245 offset:21504
	ds_read_b128 v[228:231], v245 offset:22528
	ds_read_b128 v[246:249], v245 offset:23552
	s_mov_b32 m0, s51
	s_nop 0
	buffer_load_dwordx4 v242, s[56:59], s16 offen lds
	s_add_i32 s18, s16, 0x80000
	s_mov_b32 m0, s52
	s_nop 0
	buffer_load_dwordx4 v243, s[56:59], s16 offen lds
	s_nop 0
	s_mov_b32 m0, s53
	s_nop 0
	buffer_load_dwordx4 v242, s[56:59], s18 offen lds
	s_nop 0
	s_mov_b32 m0, s55
	s_nop 0
	buffer_load_dwordx4 v243, s[56:59], s18 offen lds
	s_nop 0
	s_mov_b32 m0, s31
	s_nop 0
	buffer_load_dwordx4 v242, s[24:27], s17 offen lds
	s_nop 0
	s_mov_b32 m0, s68
	s_nop 0
	buffer_load_dwordx4 v243, s[24:27], s17 offen lds
	s_waitcnt vmcnt(24)
	s_waitcnt lgkmcnt(0)
	s_barrier
	s_setprio 1
	s_waitcnt lgkmcnt(7)
	v_mfma_f32_16x16x32_bf16 v[76:79], v[16:19], v[192:195], 0
	v_mfma_f32_16x16x32_bf16 v[68:71], v[24:27], v[192:195], 0
	s_waitcnt lgkmcnt(5)
	v_mfma_f32_16x16x32_bf16 v[60:63], v[16:19], v[200:203], 0
	v_mfma_f32_16x16x32_bf16 v[52:55], v[24:27], v[200:203], 0
	s_waitcnt lgkmcnt(3)
	v_mfma_f32_16x16x32_bf16 v[44:47], v[16:19], v[220:223], 0
	v_mfma_f32_16x16x32_bf16 v[36:39], v[24:27], v[220:223], 0
	s_waitcnt lgkmcnt(1)
	v_mfma_f32_16x16x32_bf16 v[12:15], v[16:19], v[228:231], 0
	v_mfma_f32_16x16x32_bf16 v[4:7], v[24:27], v[228:231], 0
	v_mfma_f32_16x16x32_bf16 v[76:79], v[20:23], v[196:199], v[76:79]
	v_mfma_f32_16x16x32_bf16 v[68:71], v[28:31], v[196:199], v[68:71]
	v_mfma_f32_16x16x32_bf16 v[60:63], v[20:23], v[204:207], v[60:63]
	v_mfma_f32_16x16x32_bf16 v[52:55], v[28:31], v[204:207], v[52:55]
	v_mfma_f32_16x16x32_bf16 v[44:47], v[20:23], v[224:227], v[44:47]
	v_mfma_f32_16x16x32_bf16 v[36:39], v[28:31], v[224:227], v[36:39]
	s_waitcnt lgkmcnt(0)
	v_mfma_f32_16x16x32_bf16 v[12:15], v[20:23], v[246:249], v[12:15]
	v_mfma_f32_16x16x32_bf16 v[4:7], v[28:31], v[246:249], v[4:7]
	s_setprio 0
	s_setprio 1
	v_mfma_f32_16x16x32_bf16 v[40:43], v[152:155], v[220:223], 0
	v_mfma_f32_16x16x32_bf16 v[32:35], v[168:171], v[220:223], 0
	v_mfma_f32_16x16x32_bf16 v[8:11], v[152:155], v[228:231], 0
	v_mfma_f32_16x16x32_bf16 v[0:3], v[168:171], v[228:231], 0
	v_mfma_f32_16x16x32_bf16 v[16:19], v[152:155], v[192:195], 0
	v_mfma_f32_16x16x32_bf16 v[20:23], v[168:171], v[192:195], 0
	v_mfma_f32_16x16x32_bf16 v[24:27], v[152:155], v[200:203], 0
	v_mfma_f32_16x16x32_bf16 v[28:31], v[168:171], v[200:203], 0
	v_mfma_f32_16x16x32_bf16 v[40:43], v[160:163], v[224:227], v[40:43]
	v_mfma_f32_16x16x32_bf16 v[32:35], v[176:179], v[224:227], v[32:35]
	v_mfma_f32_16x16x32_bf16 v[8:11], v[160:163], v[246:249], v[8:11]
	v_mfma_f32_16x16x32_bf16 v[0:3], v[176:179], v[246:249], v[0:3]
	v_mfma_f32_16x16x32_bf16 v[16:19], v[160:163], v[196:199], v[16:19]
	v_mfma_f32_16x16x32_bf16 v[20:23], v[176:179], v[196:199], v[20:23]
	v_mfma_f32_16x16x32_bf16 v[24:27], v[160:163], v[204:207], v[24:27]
	v_mfma_f32_16x16x32_bf16 v[28:31], v[176:179], v[204:207], v[28:31]
	s_setprio 0
	s_barrier
	v_add_u32_e32 v72, 0x18000, v83
	v_add_u32_e32 v80, 0x1c000, v83
	ds_read_b128 v[48:51], v72
	ds_read_b128 v[56:59], v72 offset:1024
	ds_read_b128 v[64:67], v72 offset:2048
	ds_read_b128 v[72:75], v72 offset:3072
	ds_read_b128 v[152:155], v80
	ds_read_b128 v[160:163], v80 offset:1024
	ds_read_b128 v[168:171], v80 offset:2048
	ds_read_b128 v[176:179], v80 offset:3072
	ds_read_b128 v[192:195], v245 offset:32768
	ds_read_b128 v[196:199], v245 offset:33792
	ds_read_b128 v[200:203], v245 offset:34816
	ds_read_b128 v[204:207], v245 offset:35840
	ds_read_b128 v[220:223], v245 offset:36864
	ds_read_b128 v[224:227], v245 offset:37888
	ds_read_b128 v[228:231], v245 offset:38912
	ds_read_b128 v[246:249], v245 offset:39936
	s_add_i32 s17, s17, 0x80000
	s_mov_b32 m0, s69
	s_nop 0
	buffer_load_dwordx4 v242, s[24:27], s17 offen lds
	s_nop 0
	s_mov_b32 m0, s70
	s_nop 0
	buffer_load_dwordx4 v243, s[24:27], s17 offen lds
	s_waitcnt vmcnt(8)
	s_waitcnt lgkmcnt(0)
	s_barrier
	s_setprio 1
	s_waitcnt lgkmcnt(7)
	v_mfma_f32_16x16x32_bf16 v[180:183], v[48:51], v[192:195], v[180:183]
	v_mfma_f32_16x16x32_bf16 v[164:167], v[64:67], v[192:195], v[164:167]
	s_waitcnt lgkmcnt(5)
	v_mfma_f32_16x16x32_bf16 v[148:151], v[48:51], v[200:203], v[148:151]
	v_mfma_f32_16x16x32_bf16 v[140:143], v[64:67], v[200:203], v[140:143]
	s_waitcnt lgkmcnt(3)
	v_mfma_f32_16x16x32_bf16 v[132:135], v[48:51], v[220:223], v[132:135]
	v_mfma_f32_16x16x32_bf16 v[124:127], v[64:67], v[220:223], v[124:127]
	s_waitcnt lgkmcnt(1)
	v_mfma_f32_16x16x32_bf16 v[116:119], v[48:51], v[228:231], v[116:119]
	v_mfma_f32_16x16x32_bf16 v[108:111], v[64:67], v[228:231], v[108:111]
	v_mfma_f32_16x16x32_bf16 v[180:183], v[56:59], v[196:199], v[180:183]
	v_mfma_f32_16x16x32_bf16 v[164:167], v[72:75], v[196:199], v[164:167]
	v_mfma_f32_16x16x32_bf16 v[148:151], v[56:59], v[204:207], v[148:151]
	v_mfma_f32_16x16x32_bf16 v[140:143], v[72:75], v[204:207], v[140:143]
	v_mfma_f32_16x16x32_bf16 v[132:135], v[56:59], v[224:227], v[132:135]
	v_mfma_f32_16x16x32_bf16 v[124:127], v[72:75], v[224:227], v[124:127]
	s_waitcnt lgkmcnt(0)
	v_mfma_f32_16x16x32_bf16 v[116:119], v[56:59], v[246:249], v[116:119]
	v_mfma_f32_16x16x32_bf16 v[108:111], v[72:75], v[246:249], v[108:111]
	s_setprio 0
	s_setprio 1
	v_mfma_f32_16x16x32_bf16 v[172:175], v[152:155], v[192:195], v[172:175]
	v_mfma_f32_16x16x32_bf16 v[156:159], v[168:171], v[192:195], v[156:159]
	v_mfma_f32_16x16x32_bf16 v[144:147], v[152:155], v[200:203], v[144:147]
	v_mfma_f32_16x16x32_bf16 v[136:139], v[168:171], v[200:203], v[136:139]
	v_mfma_f32_16x16x32_bf16 v[128:131], v[152:155], v[220:223], v[128:131]
	v_mfma_f32_16x16x32_bf16 v[120:123], v[168:171], v[220:223], v[120:123]
	v_mfma_f32_16x16x32_bf16 v[112:115], v[152:155], v[228:231], v[112:115]
	v_mfma_f32_16x16x32_bf16 v[104:107], v[168:171], v[228:231], v[104:107]
	v_mfma_f32_16x16x32_bf16 v[172:175], v[160:163], v[196:199], v[172:175]
	v_mfma_f32_16x16x32_bf16 v[156:159], v[176:179], v[196:199], v[156:159]
	v_mfma_f32_16x16x32_bf16 v[144:147], v[160:163], v[204:207], v[144:147]
	v_mfma_f32_16x16x32_bf16 v[136:139], v[176:179], v[204:207], v[136:139]
	v_mfma_f32_16x16x32_bf16 v[128:131], v[160:163], v[224:227], v[128:131]
	v_mfma_f32_16x16x32_bf16 v[120:123], v[176:179], v[224:227], v[120:123]
	v_mfma_f32_16x16x32_bf16 v[112:115], v[160:163], v[246:249], v[112:115]
	v_mfma_f32_16x16x32_bf16 v[104:107], v[176:179], v[246:249], v[104:107]
	s_setprio 0
	s_barrier
	ds_read_b128 v[192:195], v245 offset:49152
	ds_read_b128 v[196:199], v245 offset:50176
	ds_read_b128 v[200:203], v245 offset:51200
	ds_read_b128 v[204:207], v245 offset:52224
	ds_read_b128 v[220:223], v245 offset:53248
	ds_read_b128 v[224:227], v245 offset:54272
	ds_read_b128 v[228:231], v245 offset:55296
	ds_read_b128 v[246:249], v245 offset:56320
	s_or_b32 s17, s16, 0x4000
	s_mov_b32 m0, s73
	s_nop 0
	buffer_load_dwordx4 v242, s[56:59], s17 offen lds
	s_add_i32 s16, s16, 0x84000
	s_mov_b32 m0, s74
	s_nop 0
	buffer_load_dwordx4 v243, s[56:59], s17 offen lds
	s_nop 0
	s_mov_b32 m0, s77
	s_nop 0
	buffer_load_dwordx4 v242, s[56:59], s16 offen lds
	s_nop 0
	s_mov_b32 m0, s78
	s_nop 0
	buffer_load_dwordx4 v243, s[56:59], s16 offen lds
	s_nop 0
	s_mov_b32 m0, s75
	s_nop 0
	buffer_load_dwordx4 v242, s[24:27], s7 offen lds
	s_nop 0
	s_mov_b32 m0, s76
	s_nop 0
	buffer_load_dwordx4 v243, s[24:27], s7 offen lds
	s_waitcnt vmcnt(8)
	s_waitcnt lgkmcnt(0)
	s_barrier
	s_setprio 1
	s_waitcnt lgkmcnt(7)
	v_mfma_f32_16x16x32_bf16 v[76:79], v[48:51], v[192:195], v[76:79]
	v_mfma_f32_16x16x32_bf16 v[68:71], v[64:67], v[192:195], v[68:71]
	s_waitcnt lgkmcnt(5)
	v_mfma_f32_16x16x32_bf16 v[60:63], v[48:51], v[200:203], v[60:63]
	v_mfma_f32_16x16x32_bf16 v[52:55], v[64:67], v[200:203], v[52:55]
	s_waitcnt lgkmcnt(3)
	v_mfma_f32_16x16x32_bf16 v[44:47], v[48:51], v[220:223], v[44:47]
	v_mfma_f32_16x16x32_bf16 v[36:39], v[64:67], v[220:223], v[36:39]
	s_waitcnt lgkmcnt(1)
	v_mfma_f32_16x16x32_bf16 v[12:15], v[48:51], v[228:231], v[12:15]
	v_mfma_f32_16x16x32_bf16 v[4:7], v[64:67], v[228:231], v[4:7]
	v_mfma_f32_16x16x32_bf16 v[76:79], v[56:59], v[196:199], v[76:79]
	v_mfma_f32_16x16x32_bf16 v[68:71], v[72:75], v[196:199], v[68:71]
	v_mfma_f32_16x16x32_bf16 v[60:63], v[56:59], v[204:207], v[60:63]
	v_mfma_f32_16x16x32_bf16 v[52:55], v[72:75], v[204:207], v[52:55]
	v_mfma_f32_16x16x32_bf16 v[44:47], v[56:59], v[224:227], v[44:47]
	v_mfma_f32_16x16x32_bf16 v[36:39], v[72:75], v[224:227], v[36:39]
	s_waitcnt lgkmcnt(0)
	v_mfma_f32_16x16x32_bf16 v[12:15], v[56:59], v[246:249], v[12:15]
	v_mfma_f32_16x16x32_bf16 v[4:7], v[72:75], v[246:249], v[4:7]
	s_setprio 0
	s_setprio 1
	v_mfma_f32_16x16x32_bf16 v[16:19], v[152:155], v[192:195], v[16:19]
	v_mfma_f32_16x16x32_bf16 v[72:75], v[160:163], v[196:199], v[16:19]
	v_mfma_f32_16x16x32_bf16 v[16:19], v[168:171], v[192:195], v[20:23]
	v_mfma_f32_16x16x32_bf16 v[64:67], v[176:179], v[196:199], v[16:19]
	v_mfma_f32_16x16x32_bf16 v[16:19], v[152:155], v[200:203], v[24:27]
	v_mfma_f32_16x16x32_bf16 v[56:59], v[160:163], v[204:207], v[16:19]
	v_mfma_f32_16x16x32_bf16 v[16:19], v[168:171], v[200:203], v[28:31]
	v_mfma_f32_16x16x32_bf16 v[48:51], v[176:179], v[204:207], v[16:19]
	v_mfma_f32_16x16x32_bf16 v[16:19], v[152:155], v[220:223], v[40:43]
	v_mfma_f32_16x16x32_bf16 v[40:43], v[160:163], v[224:227], v[16:19]
	v_mfma_f32_16x16x32_bf16 v[16:19], v[168:171], v[220:223], v[32:35]
	v_mfma_f32_16x16x32_bf16 v[8:11], v[152:155], v[228:231], v[8:11]
	v_mfma_f32_16x16x32_bf16 v[0:3], v[168:171], v[228:231], v[0:3]
	v_mfma_f32_16x16x32_bf16 v[32:35], v[176:179], v[224:227], v[16:19]
	v_mfma_f32_16x16x32_bf16 v[8:11], v[160:163], v[246:249], v[8:11]
	v_mfma_f32_16x16x32_bf16 v[0:3], v[176:179], v[246:249], v[0:3]
	s_setprio 0
	s_barrier
	s_add_i32 s6, s6, 2
	s_add_i32 s4, s4, 0x8000
	s_add_i32 s5, s5, 0x8000

.LBB0_690:
	s_lshl_b32 s94, s92, 20
	s_and_b64 s[6:7], s[40:41], exec
	s_cselect_b32 s6, s94, s8
	s_lshl_b32 s95, s93, 20
	s_and_b64 s[10:11], s[40:41], exec
	s_cselect_b32 s7, s95, s9
	s_add_i32 s8, s8, 0x84000
	s_add_i32 s9, s9, 0x8000
	s_mov_b32 s10, -2
	s_cmp_eq_u32 s90, 1
	s_cbranch_scc0 .Lpeel_p4
	v_mov_b32_e32 v0, 0
	s_waitcnt lgkmcnt(0)
	v_mov_b32_e32 v1, v0
	v_mov_b32_e32 v2, v0
	v_mov_b32_e32 v3, v0
	v_mov_b32_e32 v4, v0
	v_mov_b32_e32 v5, v0
	v_mov_b32_e32 v6, v0
	v_mov_b32_e32 v7, v0
	v_mov_b32_e32 v16, v0
	v_mov_b32_e32 v17, v0
	v_mov_b32_e32 v18, v0
	v_mov_b32_e32 v19, v0
	v_mov_b32_e32 v20, v0
	v_mov_b32_e32 v21, v0
	v_mov_b32_e32 v22, v0
	v_mov_b32_e32 v23, v0
	v_mov_b32_e32 v32, v0
	v_mov_b32_e32 v33, v0
	v_mov_b32_e32 v34, v0
	v_mov_b32_e32 v35, v0
	v_mov_b32_e32 v36, v0
	v_mov_b32_e32 v37, v0
	v_mov_b32_e32 v38, v0
	v_mov_b32_e32 v39, v0
	s_waitcnt vmcnt(5)
	v_mov_b32_e32 v48, v0
	v_mov_b32_e32 v49, v0
	v_mov_b32_e32 v50, v0
	v_mov_b32_e32 v51, v0
	s_waitcnt vmcnt(4)
	v_mov_b32_e32 v52, v0
	v_mov_b32_e32 v53, v0
	v_mov_b32_e32 v54, v0
	v_mov_b32_e32 v55, v0
	v_mov_b32_e32 v8, v0
	v_mov_b32_e32 v9, v0
	v_mov_b32_e32 v10, v0
	v_mov_b32_e32 v11, v0
	v_mov_b32_e32 v12, v0
	v_mov_b32_e32 v13, v0
	v_mov_b32_e32 v14, v0
	v_mov_b32_e32 v15, v0
	v_mov_b32_e32 v24, v0
	v_mov_b32_e32 v25, v0
	v_mov_b32_e32 v26, v0
	v_mov_b32_e32 v27, v0
	v_mov_b32_e32 v28, v0
	v_mov_b32_e32 v29, v0
	v_mov_b32_e32 v30, v0
	v_mov_b32_e32 v31, v0
	v_mov_b32_e32 v40, v0
	v_mov_b32_e32 v41, v0
	v_mov_b32_e32 v42, v0
	v_mov_b32_e32 v43, v0
	v_mov_b32_e32 v44, v0
	v_mov_b32_e32 v45, v0
	v_mov_b32_e32 v46, v0
	v_mov_b32_e32 v47, v0
	s_waitcnt vmcnt(3)
	v_mov_b32_e32 v56, v0
	v_mov_b32_e32 v57, v0
	v_mov_b32_e32 v58, v0
	v_mov_b32_e32 v59, v0
	s_waitcnt vmcnt(2)
	v_mov_b32_e32 v60, v0
	v_mov_b32_e32 v61, v0
	v_mov_b32_e32 v62, v0
	v_mov_b32_e32 v63, v0
	v_mov_b32_e32 v64, v0
	v_mov_b32_e32 v65, v0
	v_mov_b32_e32 v66, v0
	v_mov_b32_e32 v67, v0
	v_mov_b32_e32 v68, v0
	v_mov_b32_e32 v69, v0
	v_mov_b32_e32 v70, v0
	v_mov_b32_e32 v71, v0
	v_mov_b32_e32 v104, v0
	v_mov_b32_e32 v105, v0
	v_mov_b32_e32 v106, v0
	v_mov_b32_e32 v107, v0
	v_mov_b32_e32 v108, v0
	v_mov_b32_e32 v109, v0
	v_mov_b32_e32 v110, v0
	v_mov_b32_e32 v111, v0
	v_mov_b32_e32 v120, v0
	v_mov_b32_e32 v121, v0
	v_mov_b32_e32 v122, v0
	v_mov_b32_e32 v123, v0
	v_mov_b32_e32 v124, v0
	v_mov_b32_e32 v125, v0
	v_mov_b32_e32 v126, v0
	v_mov_b32_e32 v127, v0
	v_mov_b32_e32 v144, v0
	v_mov_b32_e32 v145, v0
	v_mov_b32_e32 v146, v0
	v_mov_b32_e32 v147, v0
	v_mov_b32_e32 v148, v0
	v_mov_b32_e32 v149, v0
	v_mov_b32_e32 v150, v0
	v_mov_b32_e32 v151, v0
	v_mov_b32_e32 v72, v0
	v_mov_b32_e32 v73, v0
	v_mov_b32_e32 v74, v0
	v_mov_b32_e32 v75, v0
	v_mov_b32_e32 v76, v0
	v_mov_b32_e32 v77, v0
	v_mov_b32_e32 v78, v0
	v_mov_b32_e32 v79, v0
	v_mov_b32_e32 v112, v0
	v_mov_b32_e32 v113, v0
	v_mov_b32_e32 v114, v0
	v_mov_b32_e32 v115, v0
	v_mov_b32_e32 v116, v0
	v_mov_b32_e32 v117, v0
	v_mov_b32_e32 v118, v0
	v_mov_b32_e32 v119, v0
	v_mov_b32_e32 v132, v0
	v_mov_b32_e32 v133, v0
	v_mov_b32_e32 v134, v0
	v_mov_b32_e32 v135, v0
	v_mov_b32_e32 v136, v0
	v_mov_b32_e32 v137, v0
	v_mov_b32_e32 v138, v0
	v_mov_b32_e32 v139, v0
	v_mov_b32_e32 v160, v0
	v_mov_b32_e32 v161, v0
	v_mov_b32_e32 v162, v0
	v_mov_b32_e32 v163, v0
	v_mov_b32_e32 v164, v0
	v_mov_b32_e32 v165, v0
	v_mov_b32_e32 v166, v0
	v_mov_b32_e32 v167, v0
	s_branch .LBB0_691
.Lpeel_p4:
	s_waitcnt lgkmcnt(0)
	v_add_u32_e32 v156, 0x10000, v222
	v_add_u32_e32 v180, 0x14000, v222
	ds_read_b128 v[128:131], v156
	ds_read_b128 v[140:143], v156 offset:1024
	ds_read_b128 v[152:155], v156 offset:2048
	ds_read_b128 v[156:159], v156 offset:3072
	ds_read_b128 v[168:171], v180
	ds_read_b128 v[172:175], v180 offset:1024
	ds_read_b128 v[176:179], v180 offset:2048
	ds_read_b128 v[180:183], v180 offset:3072
	s_add_i32 s11, s8, 0xfff84000
	s_cmp_eq_u32 s10, 28
	s_cselect_b32 s13, s6, s11
	s_cselect_b32 s12, s7, s9
	s_or_b32 s11, s13, 0x4000
	ds_read_b128 v[184:187], v223
	ds_read_b128 v[188:191], v223 offset:1024
	ds_read_b128 v[192:195], v223 offset:2048
	ds_read_b128 v[196:199], v223 offset:3072
	ds_read_b128 v[200:203], v223 offset:4096
	ds_read_b128 v[204:207], v223 offset:5120
	ds_read_b128 v[224:227], v223 offset:6144
	ds_read_b128 v[228:231], v223 offset:7168
	s_mov_b32 m0, s89
	s_nop 0
	buffer_load_dwordx4 v220, s[64:67], s8 offen lds
	s_nop 0
	s_mov_b32 m0, s91
	s_nop 0
	buffer_load_dwordx4 v221, s[64:67], s8 offen lds
	s_waitcnt vmcnt(24)
	s_waitcnt lgkmcnt(0)
	s_barrier
	s_setprio 1
	s_waitcnt lgkmcnt(7)
	v_mfma_f32_16x16x32_bf16 v[164:167], v[128:131], v[184:187], 0
	v_mfma_f32_16x16x32_bf16 v[160:163], v[152:155], v[184:187], 0
	s_waitcnt lgkmcnt(5)
	v_mfma_f32_16x16x32_bf16 v[136:139], v[128:131], v[192:195], 0
	v_mfma_f32_16x16x32_bf16 v[132:135], v[152:155], v[192:195], 0
	s_waitcnt lgkmcnt(3)
	v_mfma_f32_16x16x32_bf16 v[116:119], v[128:131], v[200:203], 0
	v_mfma_f32_16x16x32_bf16 v[112:115], v[152:155], v[200:203], 0
	s_waitcnt lgkmcnt(1)
	v_mfma_f32_16x16x32_bf16 v[76:79], v[128:131], v[224:227], 0
	v_mfma_f32_16x16x32_bf16 v[72:75], v[152:155], v[224:227], 0
	v_mfma_f32_16x16x32_bf16 v[164:167], v[140:143], v[188:191], v[164:167]
	v_mfma_f32_16x16x32_bf16 v[160:163], v[156:159], v[188:191], v[160:163]
	v_mfma_f32_16x16x32_bf16 v[136:139], v[140:143], v[196:199], v[136:139]
	v_mfma_f32_16x16x32_bf16 v[132:135], v[156:159], v[196:199], v[132:135]
	v_mfma_f32_16x16x32_bf16 v[116:119], v[140:143], v[204:207], v[116:119]
	v_mfma_f32_16x16x32_bf16 v[112:115], v[156:159], v[204:207], v[112:115]
	s_waitcnt lgkmcnt(0)
	v_mfma_f32_16x16x32_bf16 v[76:79], v[140:143], v[228:231], v[76:79]
	v_mfma_f32_16x16x32_bf16 v[72:75], v[156:159], v[228:231], v[72:75]
	s_setprio 0
	s_setprio 1
	v_mfma_f32_16x16x32_bf16 v[148:151], v[168:171], v[184:187], 0
	v_mfma_f32_16x16x32_bf16 v[144:147], v[176:179], v[184:187], 0
	v_mfma_f32_16x16x32_bf16 v[124:127], v[168:171], v[192:195], 0
	v_mfma_f32_16x16x32_bf16 v[120:123], v[176:179], v[192:195], 0
	v_mfma_f32_16x16x32_bf16 v[108:111], v[168:171], v[200:203], 0
	v_mfma_f32_16x16x32_bf16 v[104:107], v[176:179], v[200:203], 0
	v_mfma_f32_16x16x32_bf16 v[68:71], v[168:171], v[224:227], 0
	v_mfma_f32_16x16x32_bf16 v[64:67], v[176:179], v[224:227], 0
	v_mfma_f32_16x16x32_bf16 v[148:151], v[172:175], v[188:191], v[148:151]
	v_mfma_f32_16x16x32_bf16 v[144:147], v[180:183], v[188:191], v[144:147]
	v_mfma_f32_16x16x32_bf16 v[124:127], v[172:175], v[196:199], v[124:127]
	v_mfma_f32_16x16x32_bf16 v[120:123], v[180:183], v[196:199], v[120:123]
	v_mfma_f32_16x16x32_bf16 v[108:111], v[172:175], v[204:207], v[108:111]
	v_mfma_f32_16x16x32_bf16 v[104:107], v[180:183], v[204:207], v[104:107]
	v_mfma_f32_16x16x32_bf16 v[68:71], v[172:175], v[228:231], v[68:71]
	v_mfma_f32_16x16x32_bf16 v[64:67], v[180:183], v[228:231], v[64:67]
	s_setprio 0
	s_barrier
	ds_read_b128 v[184:187], v223 offset:16384
	ds_read_b128 v[188:191], v223 offset:17408
	ds_read_b128 v[192:195], v223 offset:18432
	ds_read_b128 v[196:199], v223 offset:19456
	ds_read_b128 v[200:203], v223 offset:20480
	ds_read_b128 v[204:207], v223 offset:21504
	ds_read_b128 v[224:227], v223 offset:22528
	ds_read_b128 v[228:231], v223 offset:23552
	s_mov_b32 m0, s55
	s_nop 0
	buffer_load_dwordx4 v220, s[48:51], s12 offen lds
	s_add_i32 s14, s12, 0x80000
	s_mov_b32 m0, s76
	s_nop 0
	buffer_load_dwordx4 v221, s[48:51], s12 offen lds
	s_nop 0
	s_mov_b32 m0, s77
	s_nop 0
	buffer_load_dwordx4 v220, s[48:51], s14 offen lds
	s_nop 0
	s_mov_b32 m0, s78
	s_nop 0
	buffer_load_dwordx4 v221, s[48:51], s14 offen lds
	s_nop 0
	s_mov_b32 m0, s31
	s_nop 0
	buffer_load_dwordx4 v220, s[64:67], s13 offen lds
	s_nop 0
	s_mov_b32 m0, s79
	s_nop 0
	buffer_load_dwordx4 v221, s[64:67], s13 offen lds
	s_waitcnt vmcnt(24)
	s_waitcnt lgkmcnt(0)
	s_barrier
	s_setprio 1
	s_waitcnt lgkmcnt(7)
	v_mfma_f32_16x16x32_bf16 v[60:63], v[128:131], v[184:187], 0
	v_mfma_f32_16x16x32_bf16 v[56:59], v[152:155], v[184:187], 0
	s_waitcnt lgkmcnt(5)
	v_mfma_f32_16x16x32_bf16 v[44:47], v[128:131], v[192:195], 0
	v_mfma_f32_16x16x32_bf16 v[40:43], v[152:155], v[192:195], 0
	s_waitcnt lgkmcnt(3)
	v_mfma_f32_16x16x32_bf16 v[28:31], v[128:131], v[200:203], 0
	v_mfma_f32_16x16x32_bf16 v[24:27], v[152:155], v[200:203], 0
	s_waitcnt lgkmcnt(1)
	v_mfma_f32_16x16x32_bf16 v[12:15], v[128:131], v[224:227], 0
	v_mfma_f32_16x16x32_bf16 v[8:11], v[152:155], v[224:227], 0
	v_mfma_f32_16x16x32_bf16 v[60:63], v[140:143], v[188:191], v[60:63]
	v_mfma_f32_16x16x32_bf16 v[56:59], v[156:159], v[188:191], v[56:59]
	v_mfma_f32_16x16x32_bf16 v[44:47], v[140:143], v[196:199], v[44:47]
	v_mfma_f32_16x16x32_bf16 v[40:43], v[156:159], v[196:199], v[40:43]
	v_mfma_f32_16x16x32_bf16 v[28:31], v[140:143], v[204:207], v[28:31]
	v_mfma_f32_16x16x32_bf16 v[24:27], v[156:159], v[204:207], v[24:27]
	s_waitcnt lgkmcnt(0)
	v_mfma_f32_16x16x32_bf16 v[12:15], v[140:143], v[228:231], v[12:15]
	v_mfma_f32_16x16x32_bf16 v[8:11], v[156:159], v[228:231], v[8:11]
	s_setprio 0
	s_setprio 1
	v_mfma_f32_16x16x32_bf16 v[52:55], v[168:171], v[184:187], 0
	v_mfma_f32_16x16x32_bf16 v[48:51], v[176:179], v[184:187], 0
	v_mfma_f32_16x16x32_bf16 v[36:39], v[168:171], v[192:195], 0
	v_mfma_f32_16x16x32_bf16 v[32:35], v[176:179], v[192:195], 0
	v_mfma_f32_16x16x32_bf16 v[20:23], v[168:171], v[200:203], 0
	v_mfma_f32_16x16x32_bf16 v[16:19], v[176:179], v[200:203], 0
	v_mfma_f32_16x16x32_bf16 v[4:7], v[168:171], v[224:227], 0
	v_mfma_f32_16x16x32_bf16 v[0:3], v[176:179], v[224:227], 0
	v_mfma_f32_16x16x32_bf16 v[52:55], v[172:175], v[188:191], v[52:55]
	v_mfma_f32_16x16x32_bf16 v[48:51], v[180:183], v[188:191], v[48:51]
	v_mfma_f32_16x16x32_bf16 v[36:39], v[172:175], v[196:199], v[36:39]
	v_mfma_f32_16x16x32_bf16 v[32:35], v[180:183], v[196:199], v[32:35]
	v_mfma_f32_16x16x32_bf16 v[20:23], v[172:175], v[204:207], v[20:23]
	v_mfma_f32_16x16x32_bf16 v[16:19], v[180:183], v[204:207], v[16:19]
	v_mfma_f32_16x16x32_bf16 v[4:7], v[172:175], v[228:231], v[4:7]
	v_mfma_f32_16x16x32_bf16 v[0:3], v[180:183], v[228:231], v[0:3]
	s_setprio 0
	s_barrier
	v_add_u32_e32 v156, 0x18000, v222
	v_add_u32_e32 v180, 0x1c000, v222
	ds_read_b128 v[128:131], v156
	ds_read_b128 v[140:143], v156 offset:1024
	ds_read_b128 v[152:155], v156 offset:2048
	ds_read_b128 v[156:159], v156 offset:3072
	ds_read_b128 v[168:171], v180
	ds_read_b128 v[172:175], v180 offset:1024
	ds_read_b128 v[176:179], v180 offset:2048
	ds_read_b128 v[180:183], v180 offset:3072
	ds_read_b128 v[184:187], v223 offset:32768
	ds_read_b128 v[188:191], v223 offset:33792
	ds_read_b128 v[192:195], v223 offset:34816
	ds_read_b128 v[196:199], v223 offset:35840
	ds_read_b128 v[200:203], v223 offset:36864
	ds_read_b128 v[204:207], v223 offset:37888
	ds_read_b128 v[224:227], v223 offset:38912
	ds_read_b128 v[228:231], v223 offset:39936
	s_add_i32 s13, s13, 0x80000
	s_mov_b32 m0, s82
	s_nop 0
	buffer_load_dwordx4 v220, s[64:67], s13 offen lds
	s_nop 0
	s_mov_b32 m0, s83
	s_nop 0
	buffer_load_dwordx4 v221, s[64:67], s13 offen lds
	s_waitcnt vmcnt(8)
	s_waitcnt lgkmcnt(0)
	s_barrier
	s_setprio 1
	s_waitcnt lgkmcnt(7)
	v_mfma_f32_16x16x32_bf16 v[164:167], v[128:131], v[184:187], v[164:167]
	v_mfma_f32_16x16x32_bf16 v[160:163], v[152:155], v[184:187], v[160:163]
	s_waitcnt lgkmcnt(5)
	v_mfma_f32_16x16x32_bf16 v[136:139], v[128:131], v[192:195], v[136:139]
	v_mfma_f32_16x16x32_bf16 v[132:135], v[152:155], v[192:195], v[132:135]
	s_waitcnt lgkmcnt(3)
	v_mfma_f32_16x16x32_bf16 v[116:119], v[128:131], v[200:203], v[116:119]
	v_mfma_f32_16x16x32_bf16 v[112:115], v[152:155], v[200:203], v[112:115]
	s_waitcnt lgkmcnt(1)
	v_mfma_f32_16x16x32_bf16 v[76:79], v[128:131], v[224:227], v[76:79]
	v_mfma_f32_16x16x32_bf16 v[72:75], v[152:155], v[224:227], v[72:75]
	v_mfma_f32_16x16x32_bf16 v[164:167], v[140:143], v[188:191], v[164:167]
	v_mfma_f32_16x16x32_bf16 v[160:163], v[156:159], v[188:191], v[160:163]
	v_mfma_f32_16x16x32_bf16 v[136:139], v[140:143], v[196:199], v[136:139]
	v_mfma_f32_16x16x32_bf16 v[132:135], v[156:159], v[196:199], v[132:135]
	v_mfma_f32_16x16x32_bf16 v[116:119], v[140:143], v[204:207], v[116:119]
	v_mfma_f32_16x16x32_bf16 v[112:115], v[156:159], v[204:207], v[112:115]
	s_waitcnt lgkmcnt(0)
	v_mfma_f32_16x16x32_bf16 v[76:79], v[140:143], v[228:231], v[76:79]
	v_mfma_f32_16x16x32_bf16 v[72:75], v[156:159], v[228:231], v[72:75]
	s_setprio 0
	s_setprio 1
	v_mfma_f32_16x16x32_bf16 v[148:151], v[168:171], v[184:187], v[148:151]
	v_mfma_f32_16x16x32_bf16 v[144:147], v[176:179], v[184:187], v[144:147]
	v_mfma_f32_16x16x32_bf16 v[124:127], v[168:171], v[192:195], v[124:127]
	v_mfma_f32_16x16x32_bf16 v[120:123], v[176:179], v[192:195], v[120:123]
	v_mfma_f32_16x16x32_bf16 v[108:111], v[168:171], v[200:203], v[108:111]
	v_mfma_f32_16x16x32_bf16 v[104:107], v[176:179], v[200:203], v[104:107]
	v_mfma_f32_16x16x32_bf16 v[68:71], v[168:171], v[224:227], v[68:71]
	v_mfma_f32_16x16x32_bf16 v[64:67], v[176:179], v[224:227], v[64:67]
	v_mfma_f32_16x16x32_bf16 v[148:151], v[172:175], v[188:191], v[148:151]
	v_mfma_f32_16x16x32_bf16 v[144:147], v[180:183], v[188:191], v[144:147]
	v_mfma_f32_16x16x32_bf16 v[124:127], v[172:175], v[196:199], v[124:127]
	v_mfma_f32_16x16x32_bf16 v[120:123], v[180:183], v[196:199], v[120:123]
	v_mfma_f32_16x16x32_bf16 v[108:111], v[172:175], v[204:207], v[108:111]
	v_mfma_f32_16x16x32_bf16 v[104:107], v[180:183], v[204:207], v[104:107]
	v_mfma_f32_16x16x32_bf16 v[68:71], v[172:175], v[228:231], v[68:71]
	v_mfma_f32_16x16x32_bf16 v[64:67], v[180:183], v[228:231], v[64:67]
	s_setprio 0
	s_barrier
	ds_read_b128 v[184:187], v223 offset:49152
	ds_read_b128 v[188:191], v223 offset:50176
	ds_read_b128 v[192:195], v223 offset:51200
	ds_read_b128 v[196:199], v223 offset:52224
	ds_read_b128 v[200:203], v223 offset:53248
	ds_read_b128 v[204:207], v223 offset:54272
	ds_read_b128 v[224:227], v223 offset:55296
	ds_read_b128 v[228:231], v223 offset:56320
	s_or_b32 s13, s12, 0x4000
	s_mov_b32 m0, s34
	s_nop 0
	buffer_load_dwordx4 v220, s[48:51], s13 offen lds
	s_add_i32 s12, s12, 0x84000
	s_mov_b32 m0, s84
	s_nop 0
	buffer_load_dwordx4 v221, s[48:51], s13 offen lds
	s_nop 0
	s_mov_b32 m0, s87
	s_nop 0
	buffer_load_dwordx4 v220, s[48:51], s12 offen lds
	s_nop 0
	s_mov_b32 m0, s88
	s_nop 0
	buffer_load_dwordx4 v221, s[48:51], s12 offen lds
	s_nop 0
	s_mov_b32 m0, s85
	s_nop 0
	buffer_load_dwordx4 v220, s[64:67], s11 offen lds
	s_nop 0
	s_mov_b32 m0, s86
	s_nop 0
	buffer_load_dwordx4 v221, s[64:67], s11 offen lds
	s_waitcnt vmcnt(8)
	s_waitcnt lgkmcnt(0)
	s_barrier
	s_setprio 1
	s_waitcnt lgkmcnt(7)
	v_mfma_f32_16x16x32_bf16 v[60:63], v[128:131], v[184:187], v[60:63]
	v_mfma_f32_16x16x32_bf16 v[56:59], v[152:155], v[184:187], v[56:59]
	s_waitcnt lgkmcnt(5)
	v_mfma_f32_16x16x32_bf16 v[44:47], v[128:131], v[192:195], v[44:47]
	v_mfma_f32_16x16x32_bf16 v[40:43], v[152:155], v[192:195], v[40:43]
	s_waitcnt lgkmcnt(3)
	v_mfma_f32_16x16x32_bf16 v[28:31], v[128:131], v[200:203], v[28:31]
	v_mfma_f32_16x16x32_bf16 v[24:27], v[152:155], v[200:203], v[24:27]
	s_waitcnt lgkmcnt(1)
	v_mfma_f32_16x16x32_bf16 v[12:15], v[128:131], v[224:227], v[12:15]
	v_mfma_f32_16x16x32_bf16 v[8:11], v[152:155], v[224:227], v[8:11]
	v_mfma_f32_16x16x32_bf16 v[60:63], v[140:143], v[188:191], v[60:63]
	v_mfma_f32_16x16x32_bf16 v[56:59], v[156:159], v[188:191], v[56:59]
	v_mfma_f32_16x16x32_bf16 v[44:47], v[140:143], v[196:199], v[44:47]
	v_mfma_f32_16x16x32_bf16 v[40:43], v[156:159], v[196:199], v[40:43]
	v_mfma_f32_16x16x32_bf16 v[28:31], v[140:143], v[204:207], v[28:31]
	v_mfma_f32_16x16x32_bf16 v[24:27], v[156:159], v[204:207], v[24:27]
	s_waitcnt lgkmcnt(0)
	v_mfma_f32_16x16x32_bf16 v[12:15], v[140:143], v[228:231], v[12:15]
	v_mfma_f32_16x16x32_bf16 v[8:11], v[156:159], v[228:231], v[8:11]
	s_setprio 0
	s_setprio 1
	v_mfma_f32_16x16x32_bf16 v[52:55], v[168:171], v[184:187], v[52:55]
	v_mfma_f32_16x16x32_bf16 v[48:51], v[176:179], v[184:187], v[48:51]
	v_mfma_f32_16x16x32_bf16 v[36:39], v[168:171], v[192:195], v[36:39]
	v_mfma_f32_16x16x32_bf16 v[32:35], v[176:179], v[192:195], v[32:35]
	v_mfma_f32_16x16x32_bf16 v[20:23], v[168:171], v[200:203], v[20:23]
	v_mfma_f32_16x16x32_bf16 v[16:19], v[176:179], v[200:203], v[16:19]
	v_mfma_f32_16x16x32_bf16 v[4:7], v[168:171], v[224:227], v[4:7]
	v_mfma_f32_16x16x32_bf16 v[0:3], v[176:179], v[224:227], v[0:3]
	v_mfma_f32_16x16x32_bf16 v[52:55], v[172:175], v[188:191], v[52:55]
	v_mfma_f32_16x16x32_bf16 v[48:51], v[180:183], v[188:191], v[48:51]
	v_mfma_f32_16x16x32_bf16 v[36:39], v[172:175], v[196:199], v[36:39]
	v_mfma_f32_16x16x32_bf16 v[32:35], v[180:183], v[196:199], v[32:35]
	v_mfma_f32_16x16x32_bf16 v[20:23], v[172:175], v[204:207], v[20:23]
	v_mfma_f32_16x16x32_bf16 v[16:19], v[180:183], v[204:207], v[16:19]
	v_mfma_f32_16x16x32_bf16 v[4:7], v[172:175], v[228:231], v[4:7]
	v_mfma_f32_16x16x32_bf16 v[0:3], v[180:183], v[228:231], v[0:3]
	s_setprio 0
	s_barrier
	s_add_i32 s10, s10, 2
	s_add_i32 s8, s8, 0x8000
	s_add_i32 s9, s9, 0x8000

.LBB0_794:
	s_lshl_b32 s48, s45, 20
	s_and_b64 s[4:5], s[38:39], exec
	s_cselect_b32 s4, s48, s37
	s_lshl_b32 s49, s44, 20
	s_and_b64 s[52:53], s[38:39], exec
	s_cselect_b32 s5, s49, s51
	s_add_i32 s37, s37, 0x84000
	s_add_i32 s51, s51, 0x8000
	s_mov_b32 s52, -2
	s_cmp_eq_u32 s43, 1
	s_cbranch_scc0 .Lpeel_p5
	v_mov_b32_e32 v0, 0
	v_mov_b32_e32 v1, v0
	v_mov_b32_e32 v2, v0
	v_mov_b32_e32 v3, v0
	v_mov_b32_e32 v8, v0
	v_mov_b32_e32 v9, v0
	v_mov_b32_e32 v10, v0
	v_mov_b32_e32 v11, v0
	v_mov_b32_e32 v16, v0
	v_mov_b32_e32 v17, v0
	v_mov_b32_e32 v18, v0
	v_mov_b32_e32 v19, v0
	v_mov_b32_e32 v24, v0
	v_mov_b32_e32 v25, v0
	v_mov_b32_e32 v26, v0
	v_mov_b32_e32 v27, v0
	v_mov_b32_e32 v32, v0
	v_mov_b32_e32 v33, v0
	v_mov_b32_e32 v34, v0
	v_mov_b32_e32 v35, v0
	v_mov_b32_e32 v40, v0
	v_mov_b32_e32 v41, v0
	v_mov_b32_e32 v42, v0
	v_mov_b32_e32 v43, v0
	s_waitcnt vmcnt(5)
	v_mov_b32_e32 v48, v0
	v_mov_b32_e32 v49, v0
	v_mov_b32_e32 v50, v0
	v_mov_b32_e32 v51, v0
	s_waitcnt vmcnt(3)
	v_mov_b32_e32 v56, v0
	v_mov_b32_e32 v57, v0
	v_mov_b32_e32 v58, v0
	v_mov_b32_e32 v59, v0
	v_mov_b32_e32 v4, v0
	v_mov_b32_e32 v5, v0
	v_mov_b32_e32 v6, v0
	v_mov_b32_e32 v7, v0
	v_mov_b32_e32 v12, v0
	v_mov_b32_e32 v13, v0
	v_mov_b32_e32 v14, v0
	v_mov_b32_e32 v15, v0
	v_mov_b32_e32 v20, v0
	v_mov_b32_e32 v21, v0
	v_mov_b32_e32 v22, v0
	v_mov_b32_e32 v23, v0
	v_mov_b32_e32 v28, v0
	v_mov_b32_e32 v29, v0
	v_mov_b32_e32 v30, v0
	v_mov_b32_e32 v31, v0
	v_mov_b32_e32 v36, v0
	v_mov_b32_e32 v37, v0
	v_mov_b32_e32 v38, v0
	v_mov_b32_e32 v39, v0
	v_mov_b32_e32 v44, v0
	v_mov_b32_e32 v45, v0
	v_mov_b32_e32 v46, v0
	v_mov_b32_e32 v47, v0
	v_mov_b32_e32 v52, v0
	v_mov_b32_e32 v53, v0
	v_mov_b32_e32 v54, v0
	v_mov_b32_e32 v55, v0
	s_waitcnt vmcnt(2)
	v_mov_b32_e32 v60, v0
	v_mov_b32_e32 v61, v0
	v_mov_b32_e32 v62, v0
	v_mov_b32_e32 v63, v0
	v_mov_b32_e32 v64, v0
	v_mov_b32_e32 v65, v0
	v_mov_b32_e32 v66, v0
	v_mov_b32_e32 v67, v0
	v_mov_b32_e32 v72, v0
	v_mov_b32_e32 v73, v0
	v_mov_b32_e32 v74, v0
	v_mov_b32_e32 v75, v0
	v_mov_b32_e32 v104, v0
	v_mov_b32_e32 v105, v0
	v_mov_b32_e32 v106, v0
	v_mov_b32_e32 v107, v0
	v_mov_b32_e32 v112, v0
	v_mov_b32_e32 v113, v0
	v_mov_b32_e32 v114, v0
	v_mov_b32_e32 v115, v0
	v_mov_b32_e32 v120, v0
	v_mov_b32_e32 v121, v0
	v_mov_b32_e32 v122, v0
	v_mov_b32_e32 v123, v0
	v_mov_b32_e32 v128, v0
	v_mov_b32_e32 v129, v0
	v_mov_b32_e32 v130, v0
	v_mov_b32_e32 v131, v0
	v_mov_b32_e32 v136, v0
	v_mov_b32_e32 v137, v0
	v_mov_b32_e32 v138, v0
	v_mov_b32_e32 v139, v0
	v_mov_b32_e32 v144, v0
	v_mov_b32_e32 v145, v0
	v_mov_b32_e32 v146, v0
	v_mov_b32_e32 v147, v0
	v_mov_b32_e32 v68, v0
	v_mov_b32_e32 v69, v0
	v_mov_b32_e32 v70, v0
	v_mov_b32_e32 v71, v0
	v_mov_b32_e32 v76, v0
	v_mov_b32_e32 v77, v0
	v_mov_b32_e32 v78, v0
	v_mov_b32_e32 v79, v0
	v_mov_b32_e32 v108, v0
	v_mov_b32_e32 v109, v0
	v_mov_b32_e32 v110, v0
	v_mov_b32_e32 v111, v0
	v_mov_b32_e32 v116, v0
	v_mov_b32_e32 v117, v0
	v_mov_b32_e32 v118, v0
	v_mov_b32_e32 v119, v0
	v_mov_b32_e32 v124, v0
	v_mov_b32_e32 v125, v0
	v_mov_b32_e32 v126, v0
	v_mov_b32_e32 v127, v0
	v_mov_b32_e32 v132, v0
	v_mov_b32_e32 v133, v0
	v_mov_b32_e32 v134, v0
	v_mov_b32_e32 v135, v0
	v_mov_b32_e32 v140, v0
	v_mov_b32_e32 v141, v0
	v_mov_b32_e32 v142, v0
	v_mov_b32_e32 v143, v0
	v_mov_b32_e32 v148, v0
	v_mov_b32_e32 v149, v0
	v_mov_b32_e32 v150, v0
	v_mov_b32_e32 v151, v0
	s_branch .LBB0_795
.Lpeel_p5:
	s_waitcnt lgkmcnt(0)
	v_add_u32_e32 v164, 0x10000, v168
	ds_read_b128 v[152:155], v164
	ds_read_b128 v[156:159], v164 offset:1024
	ds_read_b128 v[160:163], v164 offset:2048
	ds_read_b128 v[170:173], v164 offset:3072
	v_add_u32_e32 v164, 0x14000, v168
	ds_read_b128 v[174:177], v164
	ds_read_b128 v[178:181], v164 offset:1024
	ds_read_b128 v[182:185], v164 offset:2048
	ds_read_b128 v[186:189], v164 offset:3072
	s_add_i32 s53, s37, 0xfff84000
	s_cmp_eq_u32 s52, 28
	s_cselect_b32 s56, s4, s53
	s_cselect_b32 s55, s5, s51
	s_or_b32 s53, s56, 0x4000
	ds_read_b128 v[190:193], v169
	ds_read_b128 v[194:197], v169 offset:1024
	ds_read_b128 v[198:201], v169 offset:2048
	ds_read_b128 v[202:205], v169 offset:3072
	ds_read_b128 v[220:223], v169 offset:4096
	ds_read_b128 v[224:227], v169 offset:5120
	ds_read_b128 v[228:231], v169 offset:6144
	ds_read_b128 v[240:243], v169 offset:7168
	s_mov_b32 m0, s41
	s_nop 0
	buffer_load_dwordx4 v166, s[24:27], s37 offen lds
	s_nop 0
	s_mov_b32 m0, s42
	s_nop 0
	buffer_load_dwordx4 v167, s[24:27], s37 offen lds
	s_waitcnt vmcnt(24)
	s_waitcnt lgkmcnt(0)
	s_barrier
	s_setprio 1
	s_waitcnt lgkmcnt(7)
	v_mfma_f32_16x16x32_bf16 v[148:151], v[152:155], v[190:193], 0
	v_mfma_f32_16x16x32_bf16 v[140:143], v[160:163], v[190:193], 0
	s_waitcnt lgkmcnt(5)
	v_mfma_f32_16x16x32_bf16 v[132:135], v[152:155], v[198:201], 0
	v_mfma_f32_16x16x32_bf16 v[124:127], v[160:163], v[198:201], 0
	s_waitcnt lgkmcnt(3)
	v_mfma_f32_16x16x32_bf16 v[116:119], v[152:155], v[220:223], 0
	v_mfma_f32_16x16x32_bf16 v[108:111], v[160:163], v[220:223], 0
	s_waitcnt lgkmcnt(1)
	v_mfma_f32_16x16x32_bf16 v[76:79], v[152:155], v[228:231], 0
	v_mfma_f32_16x16x32_bf16 v[68:71], v[160:163], v[228:231], 0
	v_mfma_f32_16x16x32_bf16 v[148:151], v[156:159], v[194:197], v[148:151]
	v_mfma_f32_16x16x32_bf16 v[140:143], v[170:173], v[194:197], v[140:143]
	v_mfma_f32_16x16x32_bf16 v[132:135], v[156:159], v[202:205], v[132:135]
	v_mfma_f32_16x16x32_bf16 v[124:127], v[170:173], v[202:205], v[124:127]
	v_mfma_f32_16x16x32_bf16 v[116:119], v[156:159], v[224:227], v[116:119]
	v_mfma_f32_16x16x32_bf16 v[108:111], v[170:173], v[224:227], v[108:111]
	s_waitcnt lgkmcnt(0)
	v_mfma_f32_16x16x32_bf16 v[76:79], v[156:159], v[240:243], v[76:79]
	v_mfma_f32_16x16x32_bf16 v[68:71], v[170:173], v[240:243], v[68:71]
	s_setprio 0
	s_setprio 1
	v_mfma_f32_16x16x32_bf16 v[144:147], v[174:177], v[190:193], 0
	v_mfma_f32_16x16x32_bf16 v[136:139], v[182:185], v[190:193], 0
	v_mfma_f32_16x16x32_bf16 v[128:131], v[174:177], v[198:201], 0
	v_mfma_f32_16x16x32_bf16 v[120:123], v[182:185], v[198:201], 0
	v_mfma_f32_16x16x32_bf16 v[112:115], v[174:177], v[220:223], 0
	v_mfma_f32_16x16x32_bf16 v[104:107], v[182:185], v[220:223], 0
	v_mfma_f32_16x16x32_bf16 v[72:75], v[174:177], v[228:231], 0
	v_mfma_f32_16x16x32_bf16 v[64:67], v[182:185], v[228:231], 0
	v_mfma_f32_16x16x32_bf16 v[144:147], v[178:181], v[194:197], v[144:147]
	v_mfma_f32_16x16x32_bf16 v[136:139], v[186:189], v[194:197], v[136:139]
	v_mfma_f32_16x16x32_bf16 v[128:131], v[178:181], v[202:205], v[128:131]
	v_mfma_f32_16x16x32_bf16 v[120:123], v[186:189], v[202:205], v[120:123]
	v_mfma_f32_16x16x32_bf16 v[112:115], v[178:181], v[224:227], v[112:115]
	v_mfma_f32_16x16x32_bf16 v[104:107], v[186:189], v[224:227], v[104:107]
	v_mfma_f32_16x16x32_bf16 v[72:75], v[178:181], v[240:243], v[72:75]
	v_mfma_f32_16x16x32_bf16 v[64:67], v[186:189], v[240:243], v[64:67]
	s_setprio 0
	s_barrier
	ds_read_b128 v[190:193], v169 offset:16384
	ds_read_b128 v[194:197], v169 offset:17408
	ds_read_b128 v[198:201], v169 offset:18432
	ds_read_b128 v[202:205], v169 offset:19456
	ds_read_b128 v[220:223], v169 offset:20480
	ds_read_b128 v[224:227], v169 offset:21504
	ds_read_b128 v[228:231], v169 offset:22528
	ds_read_b128 v[240:243], v169 offset:23552
	s_mov_b32 m0, s7
	s_nop 0
	buffer_load_dwordx4 v166, s[28:31], s55 offen lds
	s_add_i32 s57, s55, 0x80000
	s_mov_b32 m0, s8
	s_nop 0
	buffer_load_dwordx4 v167, s[28:31], s55 offen lds
	s_nop 0
	s_mov_b32 m0, s9
	s_nop 0
	buffer_load_dwordx4 v166, s[28:31], s57 offen lds
	s_nop 0
	s_mov_b32 m0, s10
	s_nop 0
	buffer_load_dwordx4 v167, s[28:31], s57 offen lds
	s_nop 0
	s_mov_b32 m0, s6
	s_nop 0
	buffer_load_dwordx4 v166, s[24:27], s56 offen lds
	s_nop 0
	s_mov_b32 m0, s11
	s_nop 0
	buffer_load_dwordx4 v167, s[24:27], s56 offen lds
	s_waitcnt vmcnt(24)
	s_waitcnt lgkmcnt(0)
	s_barrier
	s_setprio 1
	s_waitcnt lgkmcnt(7)
	v_mfma_f32_16x16x32_bf16 v[60:63], v[152:155], v[190:193], 0
	v_mfma_f32_16x16x32_bf16 v[52:55], v[160:163], v[190:193], 0
	s_waitcnt lgkmcnt(5)
	v_mfma_f32_16x16x32_bf16 v[44:47], v[152:155], v[198:201], 0
	v_mfma_f32_16x16x32_bf16 v[36:39], v[160:163], v[198:201], 0
	s_waitcnt lgkmcnt(3)
	v_mfma_f32_16x16x32_bf16 v[28:31], v[152:155], v[220:223], 0
	v_mfma_f32_16x16x32_bf16 v[20:23], v[160:163], v[220:223], 0
	s_waitcnt lgkmcnt(1)
	v_mfma_f32_16x16x32_bf16 v[12:15], v[152:155], v[228:231], 0
	v_mfma_f32_16x16x32_bf16 v[4:7], v[160:163], v[228:231], 0
	v_mfma_f32_16x16x32_bf16 v[60:63], v[156:159], v[194:197], v[60:63]
	v_mfma_f32_16x16x32_bf16 v[52:55], v[170:173], v[194:197], v[52:55]
	v_mfma_f32_16x16x32_bf16 v[44:47], v[156:159], v[202:205], v[44:47]
	v_mfma_f32_16x16x32_bf16 v[36:39], v[170:173], v[202:205], v[36:39]
	v_mfma_f32_16x16x32_bf16 v[28:31], v[156:159], v[224:227], v[28:31]
	v_mfma_f32_16x16x32_bf16 v[20:23], v[170:173], v[224:227], v[20:23]
	s_waitcnt lgkmcnt(0)
	v_mfma_f32_16x16x32_bf16 v[12:15], v[156:159], v[240:243], v[12:15]
	v_mfma_f32_16x16x32_bf16 v[4:7], v[170:173], v[240:243], v[4:7]
	s_setprio 0
	s_setprio 1
	v_mfma_f32_16x16x32_bf16 v[56:59], v[174:177], v[190:193], 0
	v_mfma_f32_16x16x32_bf16 v[48:51], v[182:185], v[190:193], 0
	v_mfma_f32_16x16x32_bf16 v[40:43], v[174:177], v[198:201], 0
	v_mfma_f32_16x16x32_bf16 v[32:35], v[182:185], v[198:201], 0
	v_mfma_f32_16x16x32_bf16 v[24:27], v[174:177], v[220:223], 0
	v_mfma_f32_16x16x32_bf16 v[16:19], v[182:185], v[220:223], 0
	v_mfma_f32_16x16x32_bf16 v[8:11], v[174:177], v[228:231], 0
	v_mfma_f32_16x16x32_bf16 v[0:3], v[182:185], v[228:231], 0
	v_mfma_f32_16x16x32_bf16 v[56:59], v[178:181], v[194:197], v[56:59]
	v_mfma_f32_16x16x32_bf16 v[48:51], v[186:189], v[194:197], v[48:51]
	v_mfma_f32_16x16x32_bf16 v[40:43], v[178:181], v[202:205], v[40:43]
	v_mfma_f32_16x16x32_bf16 v[32:35], v[186:189], v[202:205], v[32:35]
	v_mfma_f32_16x16x32_bf16 v[24:27], v[178:181], v[224:227], v[24:27]
	v_mfma_f32_16x16x32_bf16 v[16:19], v[186:189], v[224:227], v[16:19]
	v_mfma_f32_16x16x32_bf16 v[8:11], v[178:181], v[240:243], v[8:11]
	v_mfma_f32_16x16x32_bf16 v[0:3], v[186:189], v[240:243], v[0:3]
	s_setprio 0
	s_barrier
	v_add_u32_e32 v164, 0x18000, v168
	ds_read_b128 v[152:155], v164
	ds_read_b128 v[156:159], v164 offset:1024
	ds_read_b128 v[160:163], v164 offset:2048
	ds_read_b128 v[170:173], v164 offset:3072
	v_add_u32_e32 v164, 0x1c000, v168
	ds_read_b128 v[174:177], v164
	ds_read_b128 v[178:181], v164 offset:1024
	ds_read_b128 v[182:185], v164 offset:2048
	ds_read_b128 v[186:189], v164 offset:3072
	ds_read_b128 v[190:193], v169 offset:32768
	ds_read_b128 v[194:197], v169 offset:33792
	ds_read_b128 v[198:201], v169 offset:34816
	ds_read_b128 v[202:205], v169 offset:35840
	ds_read_b128 v[220:223], v169 offset:36864
	ds_read_b128 v[224:227], v169 offset:37888
	ds_read_b128 v[228:231], v169 offset:38912
	ds_read_b128 v[240:243], v169 offset:39936
	s_add_i32 s56, s56, 0x80000
	s_mov_b32 m0, s12
	s_nop 0
	buffer_load_dwordx4 v166, s[24:27], s56 offen lds
	s_nop 0
	s_mov_b32 m0, s13
	s_nop 0
	buffer_load_dwordx4 v167, s[24:27], s56 offen lds
	s_waitcnt vmcnt(8)
	s_waitcnt lgkmcnt(0)
	s_barrier
	s_setprio 1
	s_waitcnt lgkmcnt(7)
	v_mfma_f32_16x16x32_bf16 v[148:151], v[152:155], v[190:193], v[148:151]
	v_mfma_f32_16x16x32_bf16 v[140:143], v[160:163], v[190:193], v[140:143]
	s_waitcnt lgkmcnt(5)
	v_mfma_f32_16x16x32_bf16 v[132:135], v[152:155], v[198:201], v[132:135]
	v_mfma_f32_16x16x32_bf16 v[124:127], v[160:163], v[198:201], v[124:127]
	s_waitcnt lgkmcnt(3)
	v_mfma_f32_16x16x32_bf16 v[116:119], v[152:155], v[220:223], v[116:119]
	v_mfma_f32_16x16x32_bf16 v[108:111], v[160:163], v[220:223], v[108:111]
	s_waitcnt lgkmcnt(1)
	v_mfma_f32_16x16x32_bf16 v[76:79], v[152:155], v[228:231], v[76:79]
	v_mfma_f32_16x16x32_bf16 v[68:71], v[160:163], v[228:231], v[68:71]
	v_mfma_f32_16x16x32_bf16 v[148:151], v[156:159], v[194:197], v[148:151]
	v_mfma_f32_16x16x32_bf16 v[140:143], v[170:173], v[194:197], v[140:143]
	v_mfma_f32_16x16x32_bf16 v[132:135], v[156:159], v[202:205], v[132:135]
	v_mfma_f32_16x16x32_bf16 v[124:127], v[170:173], v[202:205], v[124:127]
	v_mfma_f32_16x16x32_bf16 v[116:119], v[156:159], v[224:227], v[116:119]
	v_mfma_f32_16x16x32_bf16 v[108:111], v[170:173], v[224:227], v[108:111]
	s_waitcnt lgkmcnt(0)
	v_mfma_f32_16x16x32_bf16 v[76:79], v[156:159], v[240:243], v[76:79]
	v_mfma_f32_16x16x32_bf16 v[68:71], v[170:173], v[240:243], v[68:71]
	s_setprio 0
	s_setprio 1
	v_mfma_f32_16x16x32_bf16 v[144:147], v[174:177], v[190:193], v[144:147]
	v_mfma_f32_16x16x32_bf16 v[136:139], v[182:185], v[190:193], v[136:139]
	v_mfma_f32_16x16x32_bf16 v[128:131], v[174:177], v[198:201], v[128:131]
	v_mfma_f32_16x16x32_bf16 v[120:123], v[182:185], v[198:201], v[120:123]
	v_mfma_f32_16x16x32_bf16 v[112:115], v[174:177], v[220:223], v[112:115]
	v_mfma_f32_16x16x32_bf16 v[104:107], v[182:185], v[220:223], v[104:107]
	v_mfma_f32_16x16x32_bf16 v[72:75], v[174:177], v[228:231], v[72:75]
	v_mfma_f32_16x16x32_bf16 v[64:67], v[182:185], v[228:231], v[64:67]
	v_mfma_f32_16x16x32_bf16 v[144:147], v[178:181], v[194:197], v[144:147]
	v_mfma_f32_16x16x32_bf16 v[136:139], v[186:189], v[194:197], v[136:139]
	v_mfma_f32_16x16x32_bf16 v[128:131], v[178:181], v[202:205], v[128:131]
	v_mfma_f32_16x16x32_bf16 v[120:123], v[186:189], v[202:205], v[120:123]
	v_mfma_f32_16x16x32_bf16 v[112:115], v[178:181], v[224:227], v[112:115]
	v_mfma_f32_16x16x32_bf16 v[104:107], v[186:189], v[224:227], v[104:107]
	v_mfma_f32_16x16x32_bf16 v[72:75], v[178:181], v[240:243], v[72:75]
	v_mfma_f32_16x16x32_bf16 v[64:67], v[186:189], v[240:243], v[64:67]
	s_setprio 0
	s_barrier
	ds_read_b128 v[190:193], v169 offset:49152
	ds_read_b128 v[194:197], v169 offset:50176
	ds_read_b128 v[198:201], v169 offset:51200
	ds_read_b128 v[202:205], v169 offset:52224
	ds_read_b128 v[220:223], v169 offset:53248
	ds_read_b128 v[224:227], v169 offset:54272
	ds_read_b128 v[228:231], v169 offset:55296
	ds_read_b128 v[240:243], v169 offset:56320
	s_or_b32 s56, s55, 0x4000
	s_mov_b32 m0, s16
	s_nop 0
	buffer_load_dwordx4 v166, s[28:31], s56 offen lds
	s_add_i32 s55, s55, 0x84000
	s_mov_b32 m0, s17
	s_nop 0
	buffer_load_dwordx4 v167, s[28:31], s56 offen lds
	s_nop 0
	s_mov_b32 m0, s34
	s_nop 0
	buffer_load_dwordx4 v166, s[28:31], s55 offen lds
	s_nop 0
	s_mov_b32 m0, s40
	s_nop 0
	buffer_load_dwordx4 v167, s[28:31], s55 offen lds
	s_nop 0
	s_mov_b32 m0, s18
	s_nop 0
	buffer_load_dwordx4 v166, s[24:27], s53 offen lds
	s_nop 0
	s_mov_b32 m0, s19
	s_nop 0
	buffer_load_dwordx4 v167, s[24:27], s53 offen lds
	s_waitcnt vmcnt(8)
	s_waitcnt lgkmcnt(0)
	s_barrier
	s_setprio 1
	s_waitcnt lgkmcnt(7)
	v_mfma_f32_16x16x32_bf16 v[60:63], v[152:155], v[190:193], v[60:63]
	v_mfma_f32_16x16x32_bf16 v[52:55], v[160:163], v[190:193], v[52:55]
	s_waitcnt lgkmcnt(5)
	v_mfma_f32_16x16x32_bf16 v[44:47], v[152:155], v[198:201], v[44:47]
	v_mfma_f32_16x16x32_bf16 v[36:39], v[160:163], v[198:201], v[36:39]
	s_waitcnt lgkmcnt(3)
	v_mfma_f32_16x16x32_bf16 v[28:31], v[152:155], v[220:223], v[28:31]
	v_mfma_f32_16x16x32_bf16 v[20:23], v[160:163], v[220:223], v[20:23]
	s_waitcnt lgkmcnt(1)
	v_mfma_f32_16x16x32_bf16 v[12:15], v[152:155], v[228:231], v[12:15]
	v_mfma_f32_16x16x32_bf16 v[4:7], v[160:163], v[228:231], v[4:7]
	v_mfma_f32_16x16x32_bf16 v[60:63], v[156:159], v[194:197], v[60:63]
	v_mfma_f32_16x16x32_bf16 v[52:55], v[170:173], v[194:197], v[52:55]
	v_mfma_f32_16x16x32_bf16 v[44:47], v[156:159], v[202:205], v[44:47]
	v_mfma_f32_16x16x32_bf16 v[36:39], v[170:173], v[202:205], v[36:39]
	v_mfma_f32_16x16x32_bf16 v[28:31], v[156:159], v[224:227], v[28:31]
	v_mfma_f32_16x16x32_bf16 v[20:23], v[170:173], v[224:227], v[20:23]
	s_waitcnt lgkmcnt(0)
	v_mfma_f32_16x16x32_bf16 v[12:15], v[156:159], v[240:243], v[12:15]
	v_mfma_f32_16x16x32_bf16 v[4:7], v[170:173], v[240:243], v[4:7]
	s_setprio 0
	s_setprio 1
	v_mfma_f32_16x16x32_bf16 v[56:59], v[174:177], v[190:193], v[56:59]
	v_mfma_f32_16x16x32_bf16 v[48:51], v[182:185], v[190:193], v[48:51]
	v_mfma_f32_16x16x32_bf16 v[40:43], v[174:177], v[198:201], v[40:43]
	v_mfma_f32_16x16x32_bf16 v[32:35], v[182:185], v[198:201], v[32:35]
	v_mfma_f32_16x16x32_bf16 v[24:27], v[174:177], v[220:223], v[24:27]
	v_mfma_f32_16x16x32_bf16 v[16:19], v[182:185], v[220:223], v[16:19]
	v_mfma_f32_16x16x32_bf16 v[8:11], v[174:177], v[228:231], v[8:11]
	v_mfma_f32_16x16x32_bf16 v[0:3], v[182:185], v[228:231], v[0:3]
	v_mfma_f32_16x16x32_bf16 v[56:59], v[178:181], v[194:197], v[56:59]
	v_mfma_f32_16x16x32_bf16 v[48:51], v[186:189], v[194:197], v[48:51]
	v_mfma_f32_16x16x32_bf16 v[40:43], v[178:181], v[202:205], v[40:43]
	v_mfma_f32_16x16x32_bf16 v[32:35], v[186:189], v[202:205], v[32:35]
	v_mfma_f32_16x16x32_bf16 v[24:27], v[178:181], v[224:227], v[24:27]
	v_mfma_f32_16x16x32_bf16 v[16:19], v[186:189], v[224:227], v[16:19]
	v_mfma_f32_16x16x32_bf16 v[8:11], v[178:181], v[240:243], v[8:11]
	v_mfma_f32_16x16x32_bf16 v[0:3], v[186:189], v[240:243], v[0:3]
	s_setprio 0
	s_barrier
	s_add_i32 s52, s52, 2
	s_add_i32 s37, s37, 0x8000
	s_add_i32 s51, s51, 0x8000

.LBB0_884:
	s_mul_i32 s92, s90, 0x2c0000
	s_and_b64 s[6:7], s[38:39], exec
	s_mul_i32 s93, s91, 0x2c0000
	s_cselect_b32 s6, s92, s8
	s_cselect_b32 s7, s93, s9
	s_add_i32 s8, s8, 0x164000
	s_add_i32 s9, s9, 0x8000
	s_mov_b32 s10, -2
	s_cmp_eq_u32 s88, 1
	s_cbranch_scc0 .Lpeel_p6
	v_mov_b32_e32 v0, 0
	s_waitcnt lgkmcnt(0)
	v_mov_b32_e32 v1, v0
	v_mov_b32_e32 v2, v0
	v_mov_b32_e32 v3, v0
	v_mov_b32_e32 v4, v0
	v_mov_b32_e32 v5, v0
	v_mov_b32_e32 v6, v0
	v_mov_b32_e32 v7, v0
	v_mov_b32_e32 v16, v0
	v_mov_b32_e32 v17, v0
	v_mov_b32_e32 v18, v0
	v_mov_b32_e32 v19, v0
	v_mov_b32_e32 v20, v0
	v_mov_b32_e32 v21, v0
	v_mov_b32_e32 v22, v0
	v_mov_b32_e32 v23, v0
	v_mov_b32_e32 v32, v0
	v_mov_b32_e32 v33, v0
	v_mov_b32_e32 v34, v0
	v_mov_b32_e32 v35, v0
	v_mov_b32_e32 v36, v0
	v_mov_b32_e32 v37, v0
	v_mov_b32_e32 v38, v0
	v_mov_b32_e32 v39, v0
	s_waitcnt vmcnt(5)
	v_mov_b32_e32 v48, v0
	v_mov_b32_e32 v49, v0
	v_mov_b32_e32 v50, v0
	v_mov_b32_e32 v51, v0
	s_waitcnt vmcnt(4)
	v_mov_b32_e32 v52, v0
	v_mov_b32_e32 v53, v0
	v_mov_b32_e32 v54, v0
	v_mov_b32_e32 v55, v0
	v_mov_b32_e32 v8, v0
	v_mov_b32_e32 v9, v0
	v_mov_b32_e32 v10, v0
	v_mov_b32_e32 v11, v0
	v_mov_b32_e32 v12, v0
	v_mov_b32_e32 v13, v0
	v_mov_b32_e32 v14, v0
	v_mov_b32_e32 v15, v0
	v_mov_b32_e32 v24, v0
	v_mov_b32_e32 v25, v0
	v_mov_b32_e32 v26, v0
	v_mov_b32_e32 v27, v0
	v_mov_b32_e32 v28, v0
	v_mov_b32_e32 v29, v0
	v_mov_b32_e32 v30, v0
	v_mov_b32_e32 v31, v0
	v_mov_b32_e32 v40, v0
	v_mov_b32_e32 v41, v0
	v_mov_b32_e32 v42, v0
	v_mov_b32_e32 v43, v0
	v_mov_b32_e32 v44, v0
	v_mov_b32_e32 v45, v0
	v_mov_b32_e32 v46, v0
	v_mov_b32_e32 v47, v0
	s_waitcnt vmcnt(3)
	v_mov_b32_e32 v56, v0
	v_mov_b32_e32 v57, v0
	v_mov_b32_e32 v58, v0
	v_mov_b32_e32 v59, v0
	s_waitcnt vmcnt(2)
	v_mov_b32_e32 v60, v0
	v_mov_b32_e32 v61, v0
	v_mov_b32_e32 v62, v0
	v_mov_b32_e32 v63, v0
	v_mov_b32_e32 v64, v0
	v_mov_b32_e32 v65, v0
	v_mov_b32_e32 v66, v0
	v_mov_b32_e32 v67, v0
	v_mov_b32_e32 v68, v0
	v_mov_b32_e32 v69, v0
	v_mov_b32_e32 v70, v0
	v_mov_b32_e32 v71, v0
	v_mov_b32_e32 v104, v0
	v_mov_b32_e32 v105, v0
	v_mov_b32_e32 v106, v0
	v_mov_b32_e32 v107, v0
	v_mov_b32_e32 v108, v0
	v_mov_b32_e32 v109, v0
	v_mov_b32_e32 v110, v0
	v_mov_b32_e32 v111, v0
	v_mov_b32_e32 v120, v0
	v_mov_b32_e32 v121, v0
	v_mov_b32_e32 v122, v0
	v_mov_b32_e32 v123, v0
	v_mov_b32_e32 v124, v0
	v_mov_b32_e32 v125, v0
	v_mov_b32_e32 v126, v0
	v_mov_b32_e32 v127, v0
	v_mov_b32_e32 v144, v0
	v_mov_b32_e32 v145, v0
	v_mov_b32_e32 v146, v0
	v_mov_b32_e32 v147, v0
	v_mov_b32_e32 v148, v0
	v_mov_b32_e32 v149, v0
	v_mov_b32_e32 v150, v0
	v_mov_b32_e32 v151, v0
	v_mov_b32_e32 v72, v0
	v_mov_b32_e32 v73, v0
	v_mov_b32_e32 v74, v0
	v_mov_b32_e32 v75, v0
	v_mov_b32_e32 v76, v0
	v_mov_b32_e32 v77, v0
	v_mov_b32_e32 v78, v0
	v_mov_b32_e32 v79, v0
	v_mov_b32_e32 v112, v0
	v_mov_b32_e32 v113, v0
	v_mov_b32_e32 v114, v0
	v_mov_b32_e32 v115, v0
	v_mov_b32_e32 v116, v0
	v_mov_b32_e32 v117, v0
	v_mov_b32_e32 v118, v0
	v_mov_b32_e32 v119, v0
	v_mov_b32_e32 v132, v0
	v_mov_b32_e32 v133, v0
	v_mov_b32_e32 v134, v0
	v_mov_b32_e32 v135, v0
	v_mov_b32_e32 v136, v0
	v_mov_b32_e32 v137, v0
	v_mov_b32_e32 v138, v0
	v_mov_b32_e32 v139, v0
	v_mov_b32_e32 v160, v0
	v_mov_b32_e32 v161, v0
	v_mov_b32_e32 v162, v0
	v_mov_b32_e32 v163, v0
	v_mov_b32_e32 v164, v0
	v_mov_b32_e32 v165, v0
	v_mov_b32_e32 v166, v0
	v_mov_b32_e32 v167, v0
	s_branch .LBB0_885
.Lpeel_p6:
	s_waitcnt lgkmcnt(0)
	v_add_u32_e32 v156, 0x10000, v222
	v_add_u32_e32 v180, 0x14000, v222
	ds_read_b128 v[128:131], v156
	ds_read_b128 v[140:143], v156 offset:1024
	ds_read_b128 v[152:155], v156 offset:2048
	ds_read_b128 v[156:159], v156 offset:3072
	ds_read_b128 v[168:171], v180
	ds_read_b128 v[172:175], v180 offset:1024
	ds_read_b128 v[176:179], v180 offset:2048
	ds_read_b128 v[180:183], v180 offset:3072
	s_add_i32 s11, s8, 0xffea4000
	s_cmpk_eq_i32 s10, 0x54
	s_cselect_b32 s13, s6, s11
	s_cselect_b32 s12, s7, s9
	s_or_b32 s11, s13, 0x4000
	ds_read_b128 v[184:187], v223
	ds_read_b128 v[188:191], v223 offset:1024
	ds_read_b128 v[192:195], v223 offset:2048
	ds_read_b128 v[196:199], v223 offset:3072
	ds_read_b128 v[200:203], v223 offset:4096
	ds_read_b128 v[204:207], v223 offset:5120
	ds_read_b128 v[224:227], v223 offset:6144
	ds_read_b128 v[228:231], v223 offset:7168
	s_mov_b32 m0, s87
	s_nop 0
	buffer_load_dwordx4 v220, s[20:23], s8 offen lds
	s_nop 0
	s_mov_b32 m0, s89
	s_nop 0
	buffer_load_dwordx4 v221, s[20:23], s8 offen lds
	s_waitcnt vmcnt(24)
	s_waitcnt lgkmcnt(0)
	s_barrier
	s_setprio 1
	s_waitcnt lgkmcnt(7)
	v_mfma_f32_16x16x32_bf16 v[164:167], v[128:131], v[184:187], 0
	v_mfma_f32_16x16x32_bf16 v[160:163], v[152:155], v[184:187], 0
	s_waitcnt lgkmcnt(5)
	v_mfma_f32_16x16x32_bf16 v[136:139], v[128:131], v[192:195], 0
	v_mfma_f32_16x16x32_bf16 v[132:135], v[152:155], v[192:195], 0
	s_waitcnt lgkmcnt(3)
	v_mfma_f32_16x16x32_bf16 v[116:119], v[128:131], v[200:203], 0
	v_mfma_f32_16x16x32_bf16 v[112:115], v[152:155], v[200:203], 0
	s_waitcnt lgkmcnt(1)
	v_mfma_f32_16x16x32_bf16 v[76:79], v[128:131], v[224:227], 0
	v_mfma_f32_16x16x32_bf16 v[72:75], v[152:155], v[224:227], 0
	v_mfma_f32_16x16x32_bf16 v[164:167], v[140:143], v[188:191], v[164:167]
	v_mfma_f32_16x16x32_bf16 v[160:163], v[156:159], v[188:191], v[160:163]
	v_mfma_f32_16x16x32_bf16 v[136:139], v[140:143], v[196:199], v[136:139]
	v_mfma_f32_16x16x32_bf16 v[132:135], v[156:159], v[196:199], v[132:135]
	v_mfma_f32_16x16x32_bf16 v[116:119], v[140:143], v[204:207], v[116:119]
	v_mfma_f32_16x16x32_bf16 v[112:115], v[156:159], v[204:207], v[112:115]
	s_waitcnt lgkmcnt(0)
	v_mfma_f32_16x16x32_bf16 v[76:79], v[140:143], v[228:231], v[76:79]
	v_mfma_f32_16x16x32_bf16 v[72:75], v[156:159], v[228:231], v[72:75]
	s_setprio 0
	s_setprio 1
	v_mfma_f32_16x16x32_bf16 v[148:151], v[168:171], v[184:187], 0
	v_mfma_f32_16x16x32_bf16 v[144:147], v[176:179], v[184:187], 0
	v_mfma_f32_16x16x32_bf16 v[124:127], v[168:171], v[192:195], 0
	v_mfma_f32_16x16x32_bf16 v[120:123], v[176:179], v[192:195], 0
	v_mfma_f32_16x16x32_bf16 v[108:111], v[168:171], v[200:203], 0
	v_mfma_f32_16x16x32_bf16 v[104:107], v[176:179], v[200:203], 0
	v_mfma_f32_16x16x32_bf16 v[68:71], v[168:171], v[224:227], 0
	v_mfma_f32_16x16x32_bf16 v[64:67], v[176:179], v[224:227], 0
	v_mfma_f32_16x16x32_bf16 v[148:151], v[172:175], v[188:191], v[148:151]
	v_mfma_f32_16x16x32_bf16 v[144:147], v[180:183], v[188:191], v[144:147]
	v_mfma_f32_16x16x32_bf16 v[124:127], v[172:175], v[196:199], v[124:127]
	v_mfma_f32_16x16x32_bf16 v[120:123], v[180:183], v[196:199], v[120:123]
	v_mfma_f32_16x16x32_bf16 v[108:111], v[172:175], v[204:207], v[108:111]
	v_mfma_f32_16x16x32_bf16 v[104:107], v[180:183], v[204:207], v[104:107]
	v_mfma_f32_16x16x32_bf16 v[68:71], v[172:175], v[228:231], v[68:71]
	v_mfma_f32_16x16x32_bf16 v[64:67], v[180:183], v[228:231], v[64:67]
	s_setprio 0
	s_barrier
	ds_read_b128 v[184:187], v223 offset:16384
	ds_read_b128 v[188:191], v223 offset:17408
	ds_read_b128 v[192:195], v223 offset:18432
	ds_read_b128 v[196:199], v223 offset:19456
	ds_read_b128 v[200:203], v223 offset:20480
	ds_read_b128 v[204:207], v223 offset:21504
	ds_read_b128 v[224:227], v223 offset:22528
	ds_read_b128 v[228:231], v223 offset:23552
	s_mov_b32 m0, s51
	s_nop 0
	buffer_load_dwordx4 v220, s[52:55], s12 offen lds
	s_add_i32 s14, s12, 0x160000
	s_mov_b32 m0, s74
	s_nop 0
	buffer_load_dwordx4 v221, s[52:55], s12 offen lds
	s_nop 0
	s_mov_b32 m0, s75
	s_nop 0
	buffer_load_dwordx4 v220, s[52:55], s14 offen lds
	s_nop 0
	s_mov_b32 m0, s76
	s_nop 0
	buffer_load_dwordx4 v221, s[52:55], s14 offen lds
	s_nop 0
	s_mov_b32 m0, s31
	s_nop 0
	buffer_load_dwordx4 v220, s[20:23], s13 offen lds
	s_nop 0
	s_mov_b32 m0, s77
	s_nop 0
	buffer_load_dwordx4 v221, s[20:23], s13 offen lds
	s_waitcnt vmcnt(24)
	s_waitcnt lgkmcnt(0)
	s_barrier
	s_setprio 1
	s_waitcnt lgkmcnt(7)
	v_mfma_f32_16x16x32_bf16 v[60:63], v[128:131], v[184:187], 0
	v_mfma_f32_16x16x32_bf16 v[56:59], v[152:155], v[184:187], 0
	s_waitcnt lgkmcnt(5)
	v_mfma_f32_16x16x32_bf16 v[44:47], v[128:131], v[192:195], 0
	v_mfma_f32_16x16x32_bf16 v[40:43], v[152:155], v[192:195], 0
	s_waitcnt lgkmcnt(3)
	v_mfma_f32_16x16x32_bf16 v[28:31], v[128:131], v[200:203], 0
	v_mfma_f32_16x16x32_bf16 v[24:27], v[152:155], v[200:203], 0
	s_waitcnt lgkmcnt(1)
	v_mfma_f32_16x16x32_bf16 v[12:15], v[128:131], v[224:227], 0
	v_mfma_f32_16x16x32_bf16 v[8:11], v[152:155], v[224:227], 0
	v_mfma_f32_16x16x32_bf16 v[60:63], v[140:143], v[188:191], v[60:63]
	v_mfma_f32_16x16x32_bf16 v[56:59], v[156:159], v[188:191], v[56:59]
	v_mfma_f32_16x16x32_bf16 v[44:47], v[140:143], v[196:199], v[44:47]
	v_mfma_f32_16x16x32_bf16 v[40:43], v[156:159], v[196:199], v[40:43]
	v_mfma_f32_16x16x32_bf16 v[28:31], v[140:143], v[204:207], v[28:31]
	v_mfma_f32_16x16x32_bf16 v[24:27], v[156:159], v[204:207], v[24:27]
	s_waitcnt lgkmcnt(0)
	v_mfma_f32_16x16x32_bf16 v[12:15], v[140:143], v[228:231], v[12:15]
	v_mfma_f32_16x16x32_bf16 v[8:11], v[156:159], v[228:231], v[8:11]
	s_setprio 0
	s_setprio 1
	v_mfma_f32_16x16x32_bf16 v[52:55], v[168:171], v[184:187], 0
	v_mfma_f32_16x16x32_bf16 v[48:51], v[176:179], v[184:187], 0
	v_mfma_f32_16x16x32_bf16 v[36:39], v[168:171], v[192:195], 0
	v_mfma_f32_16x16x32_bf16 v[32:35], v[176:179], v[192:195], 0
	v_mfma_f32_16x16x32_bf16 v[20:23], v[168:171], v[200:203], 0
	v_mfma_f32_16x16x32_bf16 v[16:19], v[176:179], v[200:203], 0
	v_mfma_f32_16x16x32_bf16 v[4:7], v[168:171], v[224:227], 0
	v_mfma_f32_16x16x32_bf16 v[0:3], v[176:179], v[224:227], 0
	v_mfma_f32_16x16x32_bf16 v[52:55], v[172:175], v[188:191], v[52:55]
	v_mfma_f32_16x16x32_bf16 v[48:51], v[180:183], v[188:191], v[48:51]
	v_mfma_f32_16x16x32_bf16 v[36:39], v[172:175], v[196:199], v[36:39]
	v_mfma_f32_16x16x32_bf16 v[32:35], v[180:183], v[196:199], v[32:35]
	v_mfma_f32_16x16x32_bf16 v[20:23], v[172:175], v[204:207], v[20:23]
	v_mfma_f32_16x16x32_bf16 v[16:19], v[180:183], v[204:207], v[16:19]
	v_mfma_f32_16x16x32_bf16 v[4:7], v[172:175], v[228:231], v[4:7]
	v_mfma_f32_16x16x32_bf16 v[0:3], v[180:183], v[228:231], v[0:3]
	s_setprio 0
	s_barrier
	v_add_u32_e32 v156, 0x18000, v222
	v_add_u32_e32 v180, 0x1c000, v222
	ds_read_b128 v[128:131], v156
	ds_read_b128 v[140:143], v156 offset:1024
	ds_read_b128 v[152:155], v156 offset:2048
	ds_read_b128 v[156:159], v156 offset:3072
	ds_read_b128 v[168:171], v180
	ds_read_b128 v[172:175], v180 offset:1024
	ds_read_b128 v[176:179], v180 offset:2048
	ds_read_b128 v[180:183], v180 offset:3072
	ds_read_b128 v[184:187], v223 offset:32768
	ds_read_b128 v[188:191], v223 offset:33792
	ds_read_b128 v[192:195], v223 offset:34816
	ds_read_b128 v[196:199], v223 offset:35840
	ds_read_b128 v[200:203], v223 offset:36864
	ds_read_b128 v[204:207], v223 offset:37888
	ds_read_b128 v[224:227], v223 offset:38912
	ds_read_b128 v[228:231], v223 offset:39936
	s_add_i32 s13, s13, 0x160000
	s_mov_b32 m0, s78
	s_nop 0
	buffer_load_dwordx4 v220, s[20:23], s13 offen lds
	s_nop 0
	s_mov_b32 m0, s79
	s_nop 0
	buffer_load_dwordx4 v221, s[20:23], s13 offen lds
	s_waitcnt vmcnt(8)
	s_waitcnt lgkmcnt(0)
	s_barrier
	s_setprio 1
	s_waitcnt lgkmcnt(7)
	v_mfma_f32_16x16x32_bf16 v[164:167], v[128:131], v[184:187], v[164:167]
	v_mfma_f32_16x16x32_bf16 v[160:163], v[152:155], v[184:187], v[160:163]
	s_waitcnt lgkmcnt(5)
	v_mfma_f32_16x16x32_bf16 v[136:139], v[128:131], v[192:195], v[136:139]
	v_mfma_f32_16x16x32_bf16 v[132:135], v[152:155], v[192:195], v[132:135]
	s_waitcnt lgkmcnt(3)
	v_mfma_f32_16x16x32_bf16 v[116:119], v[128:131], v[200:203], v[116:119]
	v_mfma_f32_16x16x32_bf16 v[112:115], v[152:155], v[200:203], v[112:115]
	s_waitcnt lgkmcnt(1)
	v_mfma_f32_16x16x32_bf16 v[76:79], v[128:131], v[224:227], v[76:79]
	v_mfma_f32_16x16x32_bf16 v[72:75], v[152:155], v[224:227], v[72:75]
	v_mfma_f32_16x16x32_bf16 v[164:167], v[140:143], v[188:191], v[164:167]
	v_mfma_f32_16x16x32_bf16 v[160:163], v[156:159], v[188:191], v[160:163]
	v_mfma_f32_16x16x32_bf16 v[136:139], v[140:143], v[196:199], v[136:139]
	v_mfma_f32_16x16x32_bf16 v[132:135], v[156:159], v[196:199], v[132:135]
	v_mfma_f32_16x16x32_bf16 v[116:119], v[140:143], v[204:207], v[116:119]
	v_mfma_f32_16x16x32_bf16 v[112:115], v[156:159], v[204:207], v[112:115]
	s_waitcnt lgkmcnt(0)
	v_mfma_f32_16x16x32_bf16 v[76:79], v[140:143], v[228:231], v[76:79]
	v_mfma_f32_16x16x32_bf16 v[72:75], v[156:159], v[228:231], v[72:75]
	s_setprio 0
	s_setprio 1
	v_mfma_f32_16x16x32_bf16 v[148:151], v[168:171], v[184:187], v[148:151]
	v_mfma_f32_16x16x32_bf16 v[144:147], v[176:179], v[184:187], v[144:147]
	v_mfma_f32_16x16x32_bf16 v[124:127], v[168:171], v[192:195], v[124:127]
	v_mfma_f32_16x16x32_bf16 v[120:123], v[176:179], v[192:195], v[120:123]
	v_mfma_f32_16x16x32_bf16 v[108:111], v[168:171], v[200:203], v[108:111]
	v_mfma_f32_16x16x32_bf16 v[104:107], v[176:179], v[200:203], v[104:107]
	v_mfma_f32_16x16x32_bf16 v[68:71], v[168:171], v[224:227], v[68:71]
	v_mfma_f32_16x16x32_bf16 v[64:67], v[176:179], v[224:227], v[64:67]
	v_mfma_f32_16x16x32_bf16 v[148:151], v[172:175], v[188:191], v[148:151]
	v_mfma_f32_16x16x32_bf16 v[144:147], v[180:183], v[188:191], v[144:147]
	v_mfma_f32_16x16x32_bf16 v[124:127], v[172:175], v[196:199], v[124:127]
	v_mfma_f32_16x16x32_bf16 v[120:123], v[180:183], v[196:199], v[120:123]
	v_mfma_f32_16x16x32_bf16 v[108:111], v[172:175], v[204:207], v[108:111]
	v_mfma_f32_16x16x32_bf16 v[104:107], v[180:183], v[204:207], v[104:107]
	v_mfma_f32_16x16x32_bf16 v[68:71], v[172:175], v[228:231], v[68:71]
	v_mfma_f32_16x16x32_bf16 v[64:67], v[180:183], v[228:231], v[64:67]
	s_setprio 0
	s_barrier
	ds_read_b128 v[184:187], v223 offset:49152
	ds_read_b128 v[188:191], v223 offset:50176
	ds_read_b128 v[192:195], v223 offset:51200
	ds_read_b128 v[196:199], v223 offset:52224
	ds_read_b128 v[200:203], v223 offset:53248
	ds_read_b128 v[204:207], v223 offset:54272
	ds_read_b128 v[224:227], v223 offset:55296
	ds_read_b128 v[228:231], v223 offset:56320
	s_or_b32 s13, s12, 0x4000
	s_mov_b32 m0, s34
	s_nop 0
	buffer_load_dwordx4 v220, s[52:55], s13 offen lds
	s_add_i32 s12, s12, 0x164000
	s_mov_b32 m0, s82
	s_nop 0
	buffer_load_dwordx4 v221, s[52:55], s13 offen lds
	s_nop 0
	s_mov_b32 m0, s85
	s_nop 0
	buffer_load_dwordx4 v220, s[52:55], s12 offen lds
	s_nop 0
	s_mov_b32 m0, s86
	s_nop 0
	buffer_load_dwordx4 v221, s[52:55], s12 offen lds
	s_nop 0
	s_mov_b32 m0, s83
	s_nop 0
	buffer_load_dwordx4 v220, s[20:23], s11 offen lds
	s_nop 0
	s_mov_b32 m0, s84
	s_nop 0
	buffer_load_dwordx4 v221, s[20:23], s11 offen lds
	s_waitcnt vmcnt(8)
	s_waitcnt lgkmcnt(0)
	s_barrier
	s_setprio 1
	s_waitcnt lgkmcnt(7)
	v_mfma_f32_16x16x32_bf16 v[60:63], v[128:131], v[184:187], v[60:63]
	v_mfma_f32_16x16x32_bf16 v[56:59], v[152:155], v[184:187], v[56:59]
	s_waitcnt lgkmcnt(5)
	v_mfma_f32_16x16x32_bf16 v[44:47], v[128:131], v[192:195], v[44:47]
	v_mfma_f32_16x16x32_bf16 v[40:43], v[152:155], v[192:195], v[40:43]
	s_waitcnt lgkmcnt(3)
	v_mfma_f32_16x16x32_bf16 v[28:31], v[128:131], v[200:203], v[28:31]
	v_mfma_f32_16x16x32_bf16 v[24:27], v[152:155], v[200:203], v[24:27]
	s_waitcnt lgkmcnt(1)
	v_mfma_f32_16x16x32_bf16 v[12:15], v[128:131], v[224:227], v[12:15]
	v_mfma_f32_16x16x32_bf16 v[8:11], v[152:155], v[224:227], v[8:11]
	v_mfma_f32_16x16x32_bf16 v[60:63], v[140:143], v[188:191], v[60:63]
	v_mfma_f32_16x16x32_bf16 v[56:59], v[156:159], v[188:191], v[56:59]
	v_mfma_f32_16x16x32_bf16 v[44:47], v[140:143], v[196:199], v[44:47]
	v_mfma_f32_16x16x32_bf16 v[40:43], v[156:159], v[196:199], v[40:43]
	v_mfma_f32_16x16x32_bf16 v[28:31], v[140:143], v[204:207], v[28:31]
	v_mfma_f32_16x16x32_bf16 v[24:27], v[156:159], v[204:207], v[24:27]
	s_waitcnt lgkmcnt(0)
	v_mfma_f32_16x16x32_bf16 v[12:15], v[140:143], v[228:231], v[12:15]
	v_mfma_f32_16x16x32_bf16 v[8:11], v[156:159], v[228:231], v[8:11]
	s_setprio 0
	s_setprio 1
	v_mfma_f32_16x16x32_bf16 v[52:55], v[168:171], v[184:187], v[52:55]
	v_mfma_f32_16x16x32_bf16 v[48:51], v[176:179], v[184:187], v[48:51]
	v_mfma_f32_16x16x32_bf16 v[36:39], v[168:171], v[192:195], v[36:39]
	v_mfma_f32_16x16x32_bf16 v[32:35], v[176:179], v[192:195], v[32:35]
	v_mfma_f32_16x16x32_bf16 v[20:23], v[168:171], v[200:203], v[20:23]
	v_mfma_f32_16x16x32_bf16 v[16:19], v[176:179], v[200:203], v[16:19]
	v_mfma_f32_16x16x32_bf16 v[4:7], v[168:171], v[224:227], v[4:7]
	v_mfma_f32_16x16x32_bf16 v[0:3], v[176:179], v[224:227], v[0:3]
	v_mfma_f32_16x16x32_bf16 v[52:55], v[172:175], v[188:191], v[52:55]
	v_mfma_f32_16x16x32_bf16 v[48:51], v[180:183], v[188:191], v[48:51]
	v_mfma_f32_16x16x32_bf16 v[36:39], v[172:175], v[196:199], v[36:39]
	v_mfma_f32_16x16x32_bf16 v[32:35], v[180:183], v[196:199], v[32:35]
	v_mfma_f32_16x16x32_bf16 v[20:23], v[172:175], v[204:207], v[20:23]
	v_mfma_f32_16x16x32_bf16 v[16:19], v[180:183], v[204:207], v[16:19]
	v_mfma_f32_16x16x32_bf16 v[4:7], v[172:175], v[228:231], v[4:7]
	v_mfma_f32_16x16x32_bf16 v[0:3], v[180:183], v[228:231], v[0:3]
	s_setprio 0
	s_barrier
	s_add_i32 s10, s10, 2
	s_add_i32 s8, s8, 0x8000
	s_add_i32 s9, s9, 0x8000
